# v15: v13 + HGRN chunk-local pass: last five loads issued before the wait; sample HGRN q staging in separate registers
# baseline (speedup 1.0000x reference)
.LBB0_929:
	s_cmp_lt_i32 s96, 5
	s_cselect_b64 s[42:43], -1, 0
	s_and_b64 s[0:1], s[42:43], s[0:1]
	s_andn2_b64 vcc, exec, s[0:1]
	s_cbranch_vccnz .LBB0_972
	s_add_u32 s46, s90, 0x48591600
	s_addc_u32 s47, s91, 0
	s_add_u32 s48, s90, 0xae1b600
	s_addc_u32 s49, s91, 0
	s_and_b32 s0, s87, 0xffffffc0
	v_mbcnt_hi_u32_b32 v135, -1, v216
	v_add_u32_e32 v64, s0, v135
	s_and_b32 s6, s94, -8
	s_movk_i32 s0, 0x80
	s_mov_b32 s3, 0
	s_and_b32 s8, s94, 7
	s_ashr_i32 s7, s6, 31
	v_cmp_gt_i32_e32 vcc, s0, v64
	v_ashrrev_i32_e32 v65, 31, v64
	v_lshrrev_b32_e32 v98, 6, v64
	v_and_b32_e32 v99, 63, v64
	s_mul_i32 s2, s6, 0x1100
	s_lshl_b32 s3, s8, 9
	s_add_u32 s2, s2, s3
	v_mul_u32_u24_e32 v100, 0x1100, v98
	v_lshl_add_u32 v100, v99, 3, v100
	v_add_u32_e32 v100, s2, v100
	s_add_u32 s10, s90, 0xd01b600
	s_addc_u32 s11, s91, 0
	global_load_dwordx2 v[102:103], v100, s[10:11]
	s_mul_i32 s4, s6, 0x880
	s_lshl_b32 s5, s8, 8
	s_add_u32 s4, s4, s5
	v_mul_u32_u24_e32 v101, 0x880, v98
	v_lshl_add_u32 v101, v99, 2, v101
	v_add_u32_e32 v101, s4, v101
	s_add_u32 s12, s90, 0x49691600
	s_addc_u32 s13, s91, 0
	global_load_dword v104, v101, s[12:13]
	v_readlane_b32 s26, v239, 17
	v_readlane_b32 s27, v239, 18
	v_and_b32_e32 v129, 0x7f, v64
	v_lshrrev_b32_e32 v122, 7, v64
	v_lshlrev_b32_e32 v123, 14, v122
	v_lshl_add_u32 v123, v129, 2, v123
	s_lshl_b32 s14, s94, 16
	s_add_u32 s16, s26, s14
	s_addc_u32 s17, s27, 0
	global_load_dword v0, v123, s[16:17]
	global_load_dword v1, v123, s[16:17] offset:512
	global_load_dword v2, v123, s[16:17] offset:1024
	global_load_dword v3, v123, s[16:17] offset:1536
	global_load_dword v4, v123, s[16:17] offset:2048
	global_load_dword v5, v123, s[16:17] offset:2560
	global_load_dword v6, v123, s[16:17] offset:3072
	global_load_dword v7, v123, s[16:17] offset:3584
	s_add_u32 s16, s16, 0x1000
	s_addc_u32 s17, s17, 0
	global_load_dword v8, v123, s[16:17]
	global_load_dword v9, v123, s[16:17] offset:512
	global_load_dword v10, v123, s[16:17] offset:1024
	global_load_dword v11, v123, s[16:17] offset:1536
	global_load_dword v12, v123, s[16:17] offset:2048
	global_load_dword v13, v123, s[16:17] offset:2560
	global_load_dword v14, v123, s[16:17] offset:3072
	global_load_dword v15, v123, s[16:17] offset:3584
	s_add_u32 s16, s16, 0x1000
	s_addc_u32 s17, s17, 0
	global_load_dword v16, v123, s[16:17]
	global_load_dword v17, v123, s[16:17] offset:512
	global_load_dword v18, v123, s[16:17] offset:1024
	global_load_dword v19, v123, s[16:17] offset:1536
	global_load_dword v20, v123, s[16:17] offset:2048
	global_load_dword v21, v123, s[16:17] offset:2560
	global_load_dword v22, v123, s[16:17] offset:3072
	global_load_dword v23, v123, s[16:17] offset:3584
	s_add_u32 s16, s16, 0x1000
	s_addc_u32 s17, s17, 0
	global_load_dword v24, v123, s[16:17]
	global_load_dword v25, v123, s[16:17] offset:512
	global_load_dword v26, v123, s[16:17] offset:1024
	global_load_dword v27, v123, s[16:17] offset:1536
	global_load_dword v28, v123, s[16:17] offset:2048
	global_load_dword v29, v123, s[16:17] offset:2560
	global_load_dword v30, v123, s[16:17] offset:3072
	global_load_dword v31, v123, s[16:17] offset:3584
	v_lshl_add_u32 v124, v129, 1, s4
	s_add_u32 s18, s90, 0x4a819600
	s_addc_u32 s19, s91, 0
	global_load_ushort v106, v124, s[18:19]
	s_add_u32 s18, s18, 0x880
	s_addc_u32 s19, s19, 0
	global_load_ushort v108, v124, s[18:19]
	s_add_u32 s18, s18, 0x880
	s_addc_u32 s19, s19, 0
	global_load_ushort v110, v124, s[18:19]
	s_add_u32 s18, s18, 0x880
	s_addc_u32 s19, s19, 0
	global_load_ushort v112, v124, s[18:19]
	s_add_u32 s18, s18, 0x880
	s_addc_u32 s19, s19, 0
	global_load_ushort v114, v124, s[18:19]
	s_add_u32 s18, s18, 0x880
	s_addc_u32 s19, s19, 0
	global_load_ushort v116, v124, s[18:19]
	s_add_u32 s18, s18, 0x880
	s_addc_u32 s19, s19, 0
	global_load_ushort v118, v124, s[18:19]
	s_add_u32 s18, s18, 0x880
	s_addc_u32 s19, s19, 0
	global_load_ushort v120, v124, s[18:19]
	v_lshlrev_b32_e32 v125, 9, v98
	v_lshl_add_u32 v125, v99, 3, v125
	s_waitcnt vmcnt(41)
	ds_write_b64 v125, v[102:103]
	s_waitcnt vmcnt(40)
	v_lshlrev_b32_e32 v100, 16, v104
	v_and_b32_e32 v101, 0xffff0000, v104
	ds_write_b64 v125, v[100:101] offset:4096
	v_lshlrev_b32_e32 v126, 7, v122
	s_waitcnt lgkmcnt(0)
	s_barrier
	v_lshlrev_b32_e32 v127, 9, v122
	v_lshl_add_u32 v127, v129, 2, v127
	v_add_u32_e32 v127, 0x2000, v127
	s_waitcnt vmcnt(0)
	v_lshlrev_b32_e32 v106, 16, v106
	v_lshlrev_b32_e32 v108, 16, v108
	v_lshlrev_b32_e32 v110, 16, v110
	v_lshlrev_b32_e32 v112, 16, v112
	v_lshlrev_b32_e32 v114, 16, v114
	v_lshlrev_b32_e32 v116, 16, v116
	v_lshlrev_b32_e32 v118, 16, v118
	v_lshlrev_b32_e32 v120, 16, v120
	ds_read_b128 v[32:35], v126 offset:0
	ds_read_b128 v[36:39], v126 offset:16
	ds_read_b128 v[40:43], v126 offset:32
	ds_read_b128 v[44:47], v126 offset:48
	ds_read_b128 v[48:51], v126 offset:64
	ds_read_b128 v[52:55], v126 offset:80
	ds_read_b128 v[56:59], v126 offset:96
	ds_read_b128 v[60:63], v126 offset:112
	ds_read_b128 v[66:69], v126 offset:4096
	ds_read_b128 v[70:73], v126 offset:4112
	ds_read_b128 v[74:77], v126 offset:4128
	ds_read_b128 v[78:81], v126 offset:4144
	s_waitcnt lgkmcnt(11)
	v_pk_add_f32 v[98:99], v[32:33], 1.0 op_sel_hi:[1,0] neg_lo:[1,0] neg_hi:[1,0]
	v_pk_mul_f32 v[98:99], v[98:99], v[106:107] op_sel_hi:[1,0]
	v_pk_fma_f32 v[0:1], v[0:1], v[32:33], v[98:99]
	v_pk_add_f32 v[100:101], v[34:35], 1.0 op_sel_hi:[1,0] neg_lo:[1,0] neg_hi:[1,0]
	v_pk_mul_f32 v[100:101], v[100:101], v[106:107] op_sel_hi:[1,0]
	v_pk_fma_f32 v[2:3], v[2:3], v[34:35], v[100:101]
	s_waitcnt lgkmcnt(10)
	v_pk_add_f32 v[102:103], v[36:37], 1.0 op_sel_hi:[1,0] neg_lo:[1,0] neg_hi:[1,0]
	v_pk_mul_f32 v[102:103], v[102:103], v[106:107] op_sel_hi:[1,0]
	v_pk_fma_f32 v[4:5], v[4:5], v[36:37], v[102:103]
	v_pk_add_f32 v[104:105], v[38:39], 1.0 op_sel_hi:[1,0] neg_lo:[1,0] neg_hi:[1,0]
	v_pk_mul_f32 v[104:105], v[104:105], v[106:107] op_sel_hi:[1,0]
	v_pk_fma_f32 v[6:7], v[6:7], v[38:39], v[104:105]
	s_waitcnt lgkmcnt(9)
	v_pk_add_f32 v[98:99], v[40:41], 1.0 op_sel_hi:[1,0] neg_lo:[1,0] neg_hi:[1,0]
	v_pk_mul_f32 v[98:99], v[98:99], v[106:107] op_sel_hi:[1,0]
	v_pk_fma_f32 v[8:9], v[8:9], v[40:41], v[98:99]
	v_pk_add_f32 v[100:101], v[42:43], 1.0 op_sel_hi:[1,0] neg_lo:[1,0] neg_hi:[1,0]
	v_pk_mul_f32 v[100:101], v[100:101], v[106:107] op_sel_hi:[1,0]
	v_pk_fma_f32 v[10:11], v[10:11], v[42:43], v[100:101]
	s_waitcnt lgkmcnt(8)
	v_pk_add_f32 v[102:103], v[44:45], 1.0 op_sel_hi:[1,0] neg_lo:[1,0] neg_hi:[1,0]
	v_pk_mul_f32 v[102:103], v[102:103], v[106:107] op_sel_hi:[1,0]
	v_pk_fma_f32 v[12:13], v[12:13], v[44:45], v[102:103]
	v_pk_add_f32 v[104:105], v[46:47], 1.0 op_sel_hi:[1,0] neg_lo:[1,0] neg_hi:[1,0]
	v_pk_mul_f32 v[104:105], v[104:105], v[106:107] op_sel_hi:[1,0]
	v_pk_fma_f32 v[14:15], v[14:15], v[46:47], v[104:105]
	ds_read_b128 v[82:85], v126 offset:4160
	ds_read_b128 v[86:89], v126 offset:4176
	ds_read_b128 v[90:93], v126 offset:4192
	ds_read_b128 v[94:97], v126 offset:4208
	s_waitcnt lgkmcnt(11)
	v_pk_add_f32 v[98:99], v[48:49], 1.0 op_sel_hi:[1,0] neg_lo:[1,0] neg_hi:[1,0]
	v_pk_mul_f32 v[98:99], v[98:99], v[106:107] op_sel_hi:[1,0]
	v_pk_fma_f32 v[16:17], v[16:17], v[48:49], v[98:99]
	v_pk_add_f32 v[100:101], v[50:51], 1.0 op_sel_hi:[1,0] neg_lo:[1,0] neg_hi:[1,0]
	v_pk_mul_f32 v[100:101], v[100:101], v[106:107] op_sel_hi:[1,0]
	v_pk_fma_f32 v[18:19], v[18:19], v[50:51], v[100:101]
	s_waitcnt lgkmcnt(10)
	v_pk_add_f32 v[102:103], v[52:53], 1.0 op_sel_hi:[1,0] neg_lo:[1,0] neg_hi:[1,0]
	v_pk_mul_f32 v[102:103], v[102:103], v[106:107] op_sel_hi:[1,0]
	v_pk_fma_f32 v[20:21], v[20:21], v[52:53], v[102:103]
	v_pk_add_f32 v[104:105], v[54:55], 1.0 op_sel_hi:[1,0] neg_lo:[1,0] neg_hi:[1,0]
	v_pk_mul_f32 v[104:105], v[104:105], v[106:107] op_sel_hi:[1,0]
	v_pk_fma_f32 v[22:23], v[22:23], v[54:55], v[104:105]
	s_waitcnt lgkmcnt(9)
	v_pk_add_f32 v[98:99], v[56:57], 1.0 op_sel_hi:[1,0] neg_lo:[1,0] neg_hi:[1,0]
	v_pk_mul_f32 v[98:99], v[98:99], v[106:107] op_sel_hi:[1,0]
	v_pk_fma_f32 v[24:25], v[24:25], v[56:57], v[98:99]
	v_pk_add_f32 v[100:101], v[58:59], 1.0 op_sel_hi:[1,0] neg_lo:[1,0] neg_hi:[1,0]
	v_pk_mul_f32 v[100:101], v[100:101], v[106:107] op_sel_hi:[1,0]
	v_pk_fma_f32 v[26:27], v[26:27], v[58:59], v[100:101]
	s_waitcnt lgkmcnt(8)
	v_pk_add_f32 v[102:103], v[60:61], 1.0 op_sel_hi:[1,0] neg_lo:[1,0] neg_hi:[1,0]
	v_pk_mul_f32 v[102:103], v[102:103], v[106:107] op_sel_hi:[1,0]
	v_pk_fma_f32 v[28:29], v[28:29], v[60:61], v[102:103]
	v_pk_add_f32 v[104:105], v[62:63], 1.0 op_sel_hi:[1,0] neg_lo:[1,0] neg_hi:[1,0]
	v_pk_mul_f32 v[104:105], v[104:105], v[106:107] op_sel_hi:[1,0]
	v_pk_fma_f32 v[30:31], v[30:31], v[62:63], v[104:105]
	s_waitcnt lgkmcnt(0)
	v_fma_f32 v128, v66, v0, 0
	v_fmac_f32_e32 v128, v67, v1
	v_fmac_f32_e32 v128, v68, v2
	v_fmac_f32_e32 v128, v69, v3
	v_fmac_f32_e32 v128, v70, v4
	v_fmac_f32_e32 v128, v71, v5
	v_fmac_f32_e32 v128, v72, v6
	v_fmac_f32_e32 v128, v73, v7
	v_fmac_f32_e32 v128, v74, v8
	v_fmac_f32_e32 v128, v75, v9
	v_fmac_f32_e32 v128, v76, v10
	v_fmac_f32_e32 v128, v77, v11
	v_fmac_f32_e32 v128, v78, v12
	v_fmac_f32_e32 v128, v79, v13
	v_fmac_f32_e32 v128, v80, v14
	v_fmac_f32_e32 v128, v81, v15
	v_fmac_f32_e32 v128, v82, v16
	v_fmac_f32_e32 v128, v83, v17
	v_fmac_f32_e32 v128, v84, v18
	v_fmac_f32_e32 v128, v85, v19
	v_fmac_f32_e32 v128, v86, v20
	v_fmac_f32_e32 v128, v87, v21
	v_fmac_f32_e32 v128, v88, v22
	v_fmac_f32_e32 v128, v89, v23
	v_fmac_f32_e32 v128, v90, v24
	v_fmac_f32_e32 v128, v91, v25
	v_fmac_f32_e32 v128, v92, v26
	v_fmac_f32_e32 v128, v93, v27
	v_fmac_f32_e32 v128, v94, v28
	v_fmac_f32_e32 v128, v95, v29
	v_fmac_f32_e32 v128, v96, v30
	v_fmac_f32_e32 v128, v97, v31
	ds_write_b32 v127, v128 offset:0
	ds_read_b128 v[32:35], v126 offset:512
	ds_read_b128 v[36:39], v126 offset:528
	ds_read_b128 v[40:43], v126 offset:544
	ds_read_b128 v[44:47], v126 offset:560
	ds_read_b128 v[48:51], v126 offset:576
	ds_read_b128 v[52:55], v126 offset:592
	ds_read_b128 v[56:59], v126 offset:608
	ds_read_b128 v[60:63], v126 offset:624
	ds_read_b128 v[66:69], v126 offset:4608
	ds_read_b128 v[70:73], v126 offset:4624
	ds_read_b128 v[74:77], v126 offset:4640
	ds_read_b128 v[78:81], v126 offset:4656
	s_waitcnt lgkmcnt(11)
	v_pk_add_f32 v[98:99], v[32:33], 1.0 op_sel_hi:[1,0] neg_lo:[1,0] neg_hi:[1,0]
	v_pk_mul_f32 v[98:99], v[98:99], v[108:109] op_sel_hi:[1,0]
	v_pk_fma_f32 v[0:1], v[0:1], v[32:33], v[98:99]
	v_pk_add_f32 v[100:101], v[34:35], 1.0 op_sel_hi:[1,0] neg_lo:[1,0] neg_hi:[1,0]
	v_pk_mul_f32 v[100:101], v[100:101], v[108:109] op_sel_hi:[1,0]
	v_pk_fma_f32 v[2:3], v[2:3], v[34:35], v[100:101]
	s_waitcnt lgkmcnt(10)
	v_pk_add_f32 v[102:103], v[36:37], 1.0 op_sel_hi:[1,0] neg_lo:[1,0] neg_hi:[1,0]
	v_pk_mul_f32 v[102:103], v[102:103], v[108:109] op_sel_hi:[1,0]
	v_pk_fma_f32 v[4:5], v[4:5], v[36:37], v[102:103]
	v_pk_add_f32 v[104:105], v[38:39], 1.0 op_sel_hi:[1,0] neg_lo:[1,0] neg_hi:[1,0]
	v_pk_mul_f32 v[104:105], v[104:105], v[108:109] op_sel_hi:[1,0]
	v_pk_fma_f32 v[6:7], v[6:7], v[38:39], v[104:105]
	s_waitcnt lgkmcnt(9)
	v_pk_add_f32 v[98:99], v[40:41], 1.0 op_sel_hi:[1,0] neg_lo:[1,0] neg_hi:[1,0]
	v_pk_mul_f32 v[98:99], v[98:99], v[108:109] op_sel_hi:[1,0]
	v_pk_fma_f32 v[8:9], v[8:9], v[40:41], v[98:99]
	v_pk_add_f32 v[100:101], v[42:43], 1.0 op_sel_hi:[1,0] neg_lo:[1,0] neg_hi:[1,0]
	v_pk_mul_f32 v[100:101], v[100:101], v[108:109] op_sel_hi:[1,0]
	v_pk_fma_f32 v[10:11], v[10:11], v[42:43], v[100:101]
	s_waitcnt lgkmcnt(8)
	v_pk_add_f32 v[102:103], v[44:45], 1.0 op_sel_hi:[1,0] neg_lo:[1,0] neg_hi:[1,0]
	v_pk_mul_f32 v[102:103], v[102:103], v[108:109] op_sel_hi:[1,0]
	v_pk_fma_f32 v[12:13], v[12:13], v[44:45], v[102:103]
	v_pk_add_f32 v[104:105], v[46:47], 1.0 op_sel_hi:[1,0] neg_lo:[1,0] neg_hi:[1,0]
	v_pk_mul_f32 v[104:105], v[104:105], v[108:109] op_sel_hi:[1,0]
	v_pk_fma_f32 v[14:15], v[14:15], v[46:47], v[104:105]
	ds_read_b128 v[82:85], v126 offset:4672
	ds_read_b128 v[86:89], v126 offset:4688
	ds_read_b128 v[90:93], v126 offset:4704
	ds_read_b128 v[94:97], v126 offset:4720
	s_waitcnt lgkmcnt(11)
	v_pk_add_f32 v[98:99], v[48:49], 1.0 op_sel_hi:[1,0] neg_lo:[1,0] neg_hi:[1,0]
	v_pk_mul_f32 v[98:99], v[98:99], v[108:109] op_sel_hi:[1,0]
	v_pk_fma_f32 v[16:17], v[16:17], v[48:49], v[98:99]
	v_pk_add_f32 v[100:101], v[50:51], 1.0 op_sel_hi:[1,0] neg_lo:[1,0] neg_hi:[1,0]
	v_pk_mul_f32 v[100:101], v[100:101], v[108:109] op_sel_hi:[1,0]
	v_pk_fma_f32 v[18:19], v[18:19], v[50:51], v[100:101]
	s_waitcnt lgkmcnt(10)
	v_pk_add_f32 v[102:103], v[52:53], 1.0 op_sel_hi:[1,0] neg_lo:[1,0] neg_hi:[1,0]
	v_pk_mul_f32 v[102:103], v[102:103], v[108:109] op_sel_hi:[1,0]
	v_pk_fma_f32 v[20:21], v[20:21], v[52:53], v[102:103]
	v_pk_add_f32 v[104:105], v[54:55], 1.0 op_sel_hi:[1,0] neg_lo:[1,0] neg_hi:[1,0]
	v_pk_mul_f32 v[104:105], v[104:105], v[108:109] op_sel_hi:[1,0]
	v_pk_fma_f32 v[22:23], v[22:23], v[54:55], v[104:105]
	s_waitcnt lgkmcnt(9)
	v_pk_add_f32 v[98:99], v[56:57], 1.0 op_sel_hi:[1,0] neg_lo:[1,0] neg_hi:[1,0]
	v_pk_mul_f32 v[98:99], v[98:99], v[108:109] op_sel_hi:[1,0]
	v_pk_fma_f32 v[24:25], v[24:25], v[56:57], v[98:99]
	v_pk_add_f32 v[100:101], v[58:59], 1.0 op_sel_hi:[1,0] neg_lo:[1,0] neg_hi:[1,0]
	v_pk_mul_f32 v[100:101], v[100:101], v[108:109] op_sel_hi:[1,0]
	v_pk_fma_f32 v[26:27], v[26:27], v[58:59], v[100:101]
	s_waitcnt lgkmcnt(8)
	v_pk_add_f32 v[102:103], v[60:61], 1.0 op_sel_hi:[1,0] neg_lo:[1,0] neg_hi:[1,0]
	v_pk_mul_f32 v[102:103], v[102:103], v[108:109] op_sel_hi:[1,0]
	v_pk_fma_f32 v[28:29], v[28:29], v[60:61], v[102:103]
	v_pk_add_f32 v[104:105], v[62:63], 1.0 op_sel_hi:[1,0] neg_lo:[1,0] neg_hi:[1,0]
	v_pk_mul_f32 v[104:105], v[104:105], v[108:109] op_sel_hi:[1,0]
	v_pk_fma_f32 v[30:31], v[30:31], v[62:63], v[104:105]
	s_waitcnt lgkmcnt(0)
	v_fma_f32 v128, v66, v0, 0
	v_fmac_f32_e32 v128, v67, v1
	v_fmac_f32_e32 v128, v68, v2
	v_fmac_f32_e32 v128, v69, v3
	v_fmac_f32_e32 v128, v70, v4
	v_fmac_f32_e32 v128, v71, v5
	v_fmac_f32_e32 v128, v72, v6
	v_fmac_f32_e32 v128, v73, v7
	v_fmac_f32_e32 v128, v74, v8
	v_fmac_f32_e32 v128, v75, v9
	v_fmac_f32_e32 v128, v76, v10
	v_fmac_f32_e32 v128, v77, v11
	v_fmac_f32_e32 v128, v78, v12
	v_fmac_f32_e32 v128, v79, v13
	v_fmac_f32_e32 v128, v80, v14
	v_fmac_f32_e32 v128, v81, v15
	v_fmac_f32_e32 v128, v82, v16
	v_fmac_f32_e32 v128, v83, v17
	v_fmac_f32_e32 v128, v84, v18
	v_fmac_f32_e32 v128, v85, v19
	v_fmac_f32_e32 v128, v86, v20
	v_fmac_f32_e32 v128, v87, v21
	v_fmac_f32_e32 v128, v88, v22
	v_fmac_f32_e32 v128, v89, v23
	v_fmac_f32_e32 v128, v90, v24
	v_fmac_f32_e32 v128, v91, v25
	v_fmac_f32_e32 v128, v92, v26
	v_fmac_f32_e32 v128, v93, v27
	v_fmac_f32_e32 v128, v94, v28
	v_fmac_f32_e32 v128, v95, v29
	v_fmac_f32_e32 v128, v96, v30
	v_fmac_f32_e32 v128, v97, v31
	ds_write_b32 v127, v128 offset:2048
	ds_read_b128 v[32:35], v126 offset:1024
	ds_read_b128 v[36:39], v126 offset:1040
	ds_read_b128 v[40:43], v126 offset:1056
	ds_read_b128 v[44:47], v126 offset:1072
	ds_read_b128 v[48:51], v126 offset:1088
	ds_read_b128 v[52:55], v126 offset:1104
	ds_read_b128 v[56:59], v126 offset:1120
	ds_read_b128 v[60:63], v126 offset:1136
	ds_read_b128 v[66:69], v126 offset:5120
	ds_read_b128 v[70:73], v126 offset:5136
	ds_read_b128 v[74:77], v126 offset:5152
	ds_read_b128 v[78:81], v126 offset:5168
	s_waitcnt lgkmcnt(11)
	v_pk_add_f32 v[98:99], v[32:33], 1.0 op_sel_hi:[1,0] neg_lo:[1,0] neg_hi:[1,0]
	v_pk_mul_f32 v[98:99], v[98:99], v[110:111] op_sel_hi:[1,0]
	v_pk_fma_f32 v[0:1], v[0:1], v[32:33], v[98:99]
	v_pk_add_f32 v[100:101], v[34:35], 1.0 op_sel_hi:[1,0] neg_lo:[1,0] neg_hi:[1,0]
	v_pk_mul_f32 v[100:101], v[100:101], v[110:111] op_sel_hi:[1,0]
	v_pk_fma_f32 v[2:3], v[2:3], v[34:35], v[100:101]
	s_waitcnt lgkmcnt(10)
	v_pk_add_f32 v[102:103], v[36:37], 1.0 op_sel_hi:[1,0] neg_lo:[1,0] neg_hi:[1,0]
	v_pk_mul_f32 v[102:103], v[102:103], v[110:111] op_sel_hi:[1,0]
	v_pk_fma_f32 v[4:5], v[4:5], v[36:37], v[102:103]
	v_pk_add_f32 v[104:105], v[38:39], 1.0 op_sel_hi:[1,0] neg_lo:[1,0] neg_hi:[1,0]
	v_pk_mul_f32 v[104:105], v[104:105], v[110:111] op_sel_hi:[1,0]
	v_pk_fma_f32 v[6:7], v[6:7], v[38:39], v[104:105]
	s_waitcnt lgkmcnt(9)
	v_pk_add_f32 v[98:99], v[40:41], 1.0 op_sel_hi:[1,0] neg_lo:[1,0] neg_hi:[1,0]
	v_pk_mul_f32 v[98:99], v[98:99], v[110:111] op_sel_hi:[1,0]
	v_pk_fma_f32 v[8:9], v[8:9], v[40:41], v[98:99]
	v_pk_add_f32 v[100:101], v[42:43], 1.0 op_sel_hi:[1,0] neg_lo:[1,0] neg_hi:[1,0]
	v_pk_mul_f32 v[100:101], v[100:101], v[110:111] op_sel_hi:[1,0]
	v_pk_fma_f32 v[10:11], v[10:11], v[42:43], v[100:101]
	s_waitcnt lgkmcnt(8)
	v_pk_add_f32 v[102:103], v[44:45], 1.0 op_sel_hi:[1,0] neg_lo:[1,0] neg_hi:[1,0]
	v_pk_mul_f32 v[102:103], v[102:103], v[110:111] op_sel_hi:[1,0]
	v_pk_fma_f32 v[12:13], v[12:13], v[44:45], v[102:103]
	v_pk_add_f32 v[104:105], v[46:47], 1.0 op_sel_hi:[1,0] neg_lo:[1,0] neg_hi:[1,0]
	v_pk_mul_f32 v[104:105], v[104:105], v[110:111] op_sel_hi:[1,0]
	v_pk_fma_f32 v[14:15], v[14:15], v[46:47], v[104:105]
	ds_read_b128 v[82:85], v126 offset:5184
	ds_read_b128 v[86:89], v126 offset:5200
	ds_read_b128 v[90:93], v126 offset:5216
	ds_read_b128 v[94:97], v126 offset:5232
	s_waitcnt lgkmcnt(11)
	v_pk_add_f32 v[98:99], v[48:49], 1.0 op_sel_hi:[1,0] neg_lo:[1,0] neg_hi:[1,0]
	v_pk_mul_f32 v[98:99], v[98:99], v[110:111] op_sel_hi:[1,0]
	v_pk_fma_f32 v[16:17], v[16:17], v[48:49], v[98:99]
	v_pk_add_f32 v[100:101], v[50:51], 1.0 op_sel_hi:[1,0] neg_lo:[1,0] neg_hi:[1,0]
	v_pk_mul_f32 v[100:101], v[100:101], v[110:111] op_sel_hi:[1,0]
	v_pk_fma_f32 v[18:19], v[18:19], v[50:51], v[100:101]
	s_waitcnt lgkmcnt(10)
	v_pk_add_f32 v[102:103], v[52:53], 1.0 op_sel_hi:[1,0] neg_lo:[1,0] neg_hi:[1,0]
	v_pk_mul_f32 v[102:103], v[102:103], v[110:111] op_sel_hi:[1,0]
	v_pk_fma_f32 v[20:21], v[20:21], v[52:53], v[102:103]
	v_pk_add_f32 v[104:105], v[54:55], 1.0 op_sel_hi:[1,0] neg_lo:[1,0] neg_hi:[1,0]
	v_pk_mul_f32 v[104:105], v[104:105], v[110:111] op_sel_hi:[1,0]
	v_pk_fma_f32 v[22:23], v[22:23], v[54:55], v[104:105]
	s_waitcnt lgkmcnt(9)
	v_pk_add_f32 v[98:99], v[56:57], 1.0 op_sel_hi:[1,0] neg_lo:[1,0] neg_hi:[1,0]
	v_pk_mul_f32 v[98:99], v[98:99], v[110:111] op_sel_hi:[1,0]
	v_pk_fma_f32 v[24:25], v[24:25], v[56:57], v[98:99]
	v_pk_add_f32 v[100:101], v[58:59], 1.0 op_sel_hi:[1,0] neg_lo:[1,0] neg_hi:[1,0]
	v_pk_mul_f32 v[100:101], v[100:101], v[110:111] op_sel_hi:[1,0]
	v_pk_fma_f32 v[26:27], v[26:27], v[58:59], v[100:101]
	s_waitcnt lgkmcnt(8)
	v_pk_add_f32 v[102:103], v[60:61], 1.0 op_sel_hi:[1,0] neg_lo:[1,0] neg_hi:[1,0]
	v_pk_mul_f32 v[102:103], v[102:103], v[110:111] op_sel_hi:[1,0]
	v_pk_fma_f32 v[28:29], v[28:29], v[60:61], v[102:103]
	v_pk_add_f32 v[104:105], v[62:63], 1.0 op_sel_hi:[1,0] neg_lo:[1,0] neg_hi:[1,0]
	v_pk_mul_f32 v[104:105], v[104:105], v[110:111] op_sel_hi:[1,0]
	v_pk_fma_f32 v[30:31], v[30:31], v[62:63], v[104:105]
	s_waitcnt lgkmcnt(0)
	v_fma_f32 v128, v66, v0, 0
	v_fmac_f32_e32 v128, v67, v1
	v_fmac_f32_e32 v128, v68, v2
	v_fmac_f32_e32 v128, v69, v3
	v_fmac_f32_e32 v128, v70, v4
	v_fmac_f32_e32 v128, v71, v5
	v_fmac_f32_e32 v128, v72, v6
	v_fmac_f32_e32 v128, v73, v7
	v_fmac_f32_e32 v128, v74, v8
	v_fmac_f32_e32 v128, v75, v9
	v_fmac_f32_e32 v128, v76, v10
	v_fmac_f32_e32 v128, v77, v11
	v_fmac_f32_e32 v128, v78, v12
	v_fmac_f32_e32 v128, v79, v13
	v_fmac_f32_e32 v128, v80, v14
	v_fmac_f32_e32 v128, v81, v15
	v_fmac_f32_e32 v128, v82, v16
	v_fmac_f32_e32 v128, v83, v17
	v_fmac_f32_e32 v128, v84, v18
	v_fmac_f32_e32 v128, v85, v19
	v_fmac_f32_e32 v128, v86, v20
	v_fmac_f32_e32 v128, v87, v21
	v_fmac_f32_e32 v128, v88, v22
	v_fmac_f32_e32 v128, v89, v23
	v_fmac_f32_e32 v128, v90, v24
	v_fmac_f32_e32 v128, v91, v25
	v_fmac_f32_e32 v128, v92, v26
	v_fmac_f32_e32 v128, v93, v27
	v_fmac_f32_e32 v128, v94, v28
	v_fmac_f32_e32 v128, v95, v29
	v_fmac_f32_e32 v128, v96, v30
	v_fmac_f32_e32 v128, v97, v31
	ds_write_b32 v127, v128 offset:4096
	ds_read_b128 v[32:35], v126 offset:1536
	ds_read_b128 v[36:39], v126 offset:1552
	ds_read_b128 v[40:43], v126 offset:1568
	ds_read_b128 v[44:47], v126 offset:1584
	ds_read_b128 v[48:51], v126 offset:1600
	ds_read_b128 v[52:55], v126 offset:1616
	ds_read_b128 v[56:59], v126 offset:1632
	ds_read_b128 v[60:63], v126 offset:1648
	ds_read_b128 v[66:69], v126 offset:5632
	ds_read_b128 v[70:73], v126 offset:5648
	ds_read_b128 v[74:77], v126 offset:5664
	ds_read_b128 v[78:81], v126 offset:5680
	s_waitcnt lgkmcnt(11)
	v_pk_add_f32 v[98:99], v[32:33], 1.0 op_sel_hi:[1,0] neg_lo:[1,0] neg_hi:[1,0]
	v_pk_mul_f32 v[98:99], v[98:99], v[112:113] op_sel_hi:[1,0]
	v_pk_fma_f32 v[0:1], v[0:1], v[32:33], v[98:99]
	v_pk_add_f32 v[100:101], v[34:35], 1.0 op_sel_hi:[1,0] neg_lo:[1,0] neg_hi:[1,0]
	v_pk_mul_f32 v[100:101], v[100:101], v[112:113] op_sel_hi:[1,0]
	v_pk_fma_f32 v[2:3], v[2:3], v[34:35], v[100:101]
	s_waitcnt lgkmcnt(10)
	v_pk_add_f32 v[102:103], v[36:37], 1.0 op_sel_hi:[1,0] neg_lo:[1,0] neg_hi:[1,0]
	v_pk_mul_f32 v[102:103], v[102:103], v[112:113] op_sel_hi:[1,0]
	v_pk_fma_f32 v[4:5], v[4:5], v[36:37], v[102:103]
	v_pk_add_f32 v[104:105], v[38:39], 1.0 op_sel_hi:[1,0] neg_lo:[1,0] neg_hi:[1,0]
	v_pk_mul_f32 v[104:105], v[104:105], v[112:113] op_sel_hi:[1,0]
	v_pk_fma_f32 v[6:7], v[6:7], v[38:39], v[104:105]
	s_waitcnt lgkmcnt(9)
	v_pk_add_f32 v[98:99], v[40:41], 1.0 op_sel_hi:[1,0] neg_lo:[1,0] neg_hi:[1,0]
	v_pk_mul_f32 v[98:99], v[98:99], v[112:113] op_sel_hi:[1,0]
	v_pk_fma_f32 v[8:9], v[8:9], v[40:41], v[98:99]
	v_pk_add_f32 v[100:101], v[42:43], 1.0 op_sel_hi:[1,0] neg_lo:[1,0] neg_hi:[1,0]
	v_pk_mul_f32 v[100:101], v[100:101], v[112:113] op_sel_hi:[1,0]
	v_pk_fma_f32 v[10:11], v[10:11], v[42:43], v[100:101]
	s_waitcnt lgkmcnt(8)
	v_pk_add_f32 v[102:103], v[44:45], 1.0 op_sel_hi:[1,0] neg_lo:[1,0] neg_hi:[1,0]
	v_pk_mul_f32 v[102:103], v[102:103], v[112:113] op_sel_hi:[1,0]
	v_pk_fma_f32 v[12:13], v[12:13], v[44:45], v[102:103]
	v_pk_add_f32 v[104:105], v[46:47], 1.0 op_sel_hi:[1,0] neg_lo:[1,0] neg_hi:[1,0]
	v_pk_mul_f32 v[104:105], v[104:105], v[112:113] op_sel_hi:[1,0]
	v_pk_fma_f32 v[14:15], v[14:15], v[46:47], v[104:105]
	ds_read_b128 v[82:85], v126 offset:5696
	ds_read_b128 v[86:89], v126 offset:5712
	ds_read_b128 v[90:93], v126 offset:5728
	ds_read_b128 v[94:97], v126 offset:5744
	s_waitcnt lgkmcnt(11)
	v_pk_add_f32 v[98:99], v[48:49], 1.0 op_sel_hi:[1,0] neg_lo:[1,0] neg_hi:[1,0]
	v_pk_mul_f32 v[98:99], v[98:99], v[112:113] op_sel_hi:[1,0]
	v_pk_fma_f32 v[16:17], v[16:17], v[48:49], v[98:99]
	v_pk_add_f32 v[100:101], v[50:51], 1.0 op_sel_hi:[1,0] neg_lo:[1,0] neg_hi:[1,0]
	v_pk_mul_f32 v[100:101], v[100:101], v[112:113] op_sel_hi:[1,0]
	v_pk_fma_f32 v[18:19], v[18:19], v[50:51], v[100:101]
	s_waitcnt lgkmcnt(10)
	v_pk_add_f32 v[102:103], v[52:53], 1.0 op_sel_hi:[1,0] neg_lo:[1,0] neg_hi:[1,0]
	v_pk_mul_f32 v[102:103], v[102:103], v[112:113] op_sel_hi:[1,0]
	v_pk_fma_f32 v[20:21], v[20:21], v[52:53], v[102:103]
	v_pk_add_f32 v[104:105], v[54:55], 1.0 op_sel_hi:[1,0] neg_lo:[1,0] neg_hi:[1,0]
	v_pk_mul_f32 v[104:105], v[104:105], v[112:113] op_sel_hi:[1,0]
	v_pk_fma_f32 v[22:23], v[22:23], v[54:55], v[104:105]
	s_waitcnt lgkmcnt(9)
	v_pk_add_f32 v[98:99], v[56:57], 1.0 op_sel_hi:[1,0] neg_lo:[1,0] neg_hi:[1,0]
	v_pk_mul_f32 v[98:99], v[98:99], v[112:113] op_sel_hi:[1,0]
	v_pk_fma_f32 v[24:25], v[24:25], v[56:57], v[98:99]
	v_pk_add_f32 v[100:101], v[58:59], 1.0 op_sel_hi:[1,0] neg_lo:[1,0] neg_hi:[1,0]
	v_pk_mul_f32 v[100:101], v[100:101], v[112:113] op_sel_hi:[1,0]
	v_pk_fma_f32 v[26:27], v[26:27], v[58:59], v[100:101]
	s_waitcnt lgkmcnt(8)
	v_pk_add_f32 v[102:103], v[60:61], 1.0 op_sel_hi:[1,0] neg_lo:[1,0] neg_hi:[1,0]
	v_pk_mul_f32 v[102:103], v[102:103], v[112:113] op_sel_hi:[1,0]
	v_pk_fma_f32 v[28:29], v[28:29], v[60:61], v[102:103]
	v_pk_add_f32 v[104:105], v[62:63], 1.0 op_sel_hi:[1,0] neg_lo:[1,0] neg_hi:[1,0]
	v_pk_mul_f32 v[104:105], v[104:105], v[112:113] op_sel_hi:[1,0]
	v_pk_fma_f32 v[30:31], v[30:31], v[62:63], v[104:105]
	s_waitcnt lgkmcnt(0)
	v_fma_f32 v128, v66, v0, 0
	v_fmac_f32_e32 v128, v67, v1
	v_fmac_f32_e32 v128, v68, v2
	v_fmac_f32_e32 v128, v69, v3
	v_fmac_f32_e32 v128, v70, v4
	v_fmac_f32_e32 v128, v71, v5
	v_fmac_f32_e32 v128, v72, v6
	v_fmac_f32_e32 v128, v73, v7
	v_fmac_f32_e32 v128, v74, v8
	v_fmac_f32_e32 v128, v75, v9
	v_fmac_f32_e32 v128, v76, v10
	v_fmac_f32_e32 v128, v77, v11
	v_fmac_f32_e32 v128, v78, v12
	v_fmac_f32_e32 v128, v79, v13
	v_fmac_f32_e32 v128, v80, v14
	v_fmac_f32_e32 v128, v81, v15
	v_fmac_f32_e32 v128, v82, v16
	v_fmac_f32_e32 v128, v83, v17
	v_fmac_f32_e32 v128, v84, v18
	v_fmac_f32_e32 v128, v85, v19
	v_fmac_f32_e32 v128, v86, v20
	v_fmac_f32_e32 v128, v87, v21
	v_fmac_f32_e32 v128, v88, v22
	v_fmac_f32_e32 v128, v89, v23
	v_fmac_f32_e32 v128, v90, v24
	v_fmac_f32_e32 v128, v91, v25
	v_fmac_f32_e32 v128, v92, v26
	v_fmac_f32_e32 v128, v93, v27
	v_fmac_f32_e32 v128, v94, v28
	v_fmac_f32_e32 v128, v95, v29
	v_fmac_f32_e32 v128, v96, v30
	v_fmac_f32_e32 v128, v97, v31
	ds_write_b32 v127, v128 offset:6144
	ds_read_b128 v[32:35], v126 offset:2048
	ds_read_b128 v[36:39], v126 offset:2064
	ds_read_b128 v[40:43], v126 offset:2080
	ds_read_b128 v[44:47], v126 offset:2096
	ds_read_b128 v[48:51], v126 offset:2112
	ds_read_b128 v[52:55], v126 offset:2128
	ds_read_b128 v[56:59], v126 offset:2144
	ds_read_b128 v[60:63], v126 offset:2160
	ds_read_b128 v[66:69], v126 offset:6144
	ds_read_b128 v[70:73], v126 offset:6160
	ds_read_b128 v[74:77], v126 offset:6176
	ds_read_b128 v[78:81], v126 offset:6192
	s_waitcnt lgkmcnt(11)
	v_pk_add_f32 v[98:99], v[32:33], 1.0 op_sel_hi:[1,0] neg_lo:[1,0] neg_hi:[1,0]
	v_pk_mul_f32 v[98:99], v[98:99], v[114:115] op_sel_hi:[1,0]
	v_pk_fma_f32 v[0:1], v[0:1], v[32:33], v[98:99]
	v_pk_add_f32 v[100:101], v[34:35], 1.0 op_sel_hi:[1,0] neg_lo:[1,0] neg_hi:[1,0]
	v_pk_mul_f32 v[100:101], v[100:101], v[114:115] op_sel_hi:[1,0]
	v_pk_fma_f32 v[2:3], v[2:3], v[34:35], v[100:101]
	s_waitcnt lgkmcnt(10)
	v_pk_add_f32 v[102:103], v[36:37], 1.0 op_sel_hi:[1,0] neg_lo:[1,0] neg_hi:[1,0]
	v_pk_mul_f32 v[102:103], v[102:103], v[114:115] op_sel_hi:[1,0]
	v_pk_fma_f32 v[4:5], v[4:5], v[36:37], v[102:103]
	v_pk_add_f32 v[104:105], v[38:39], 1.0 op_sel_hi:[1,0] neg_lo:[1,0] neg_hi:[1,0]
	v_pk_mul_f32 v[104:105], v[104:105], v[114:115] op_sel_hi:[1,0]
	v_pk_fma_f32 v[6:7], v[6:7], v[38:39], v[104:105]
	s_waitcnt lgkmcnt(9)
	v_pk_add_f32 v[98:99], v[40:41], 1.0 op_sel_hi:[1,0] neg_lo:[1,0] neg_hi:[1,0]
	v_pk_mul_f32 v[98:99], v[98:99], v[114:115] op_sel_hi:[1,0]
	v_pk_fma_f32 v[8:9], v[8:9], v[40:41], v[98:99]
	v_pk_add_f32 v[100:101], v[42:43], 1.0 op_sel_hi:[1,0] neg_lo:[1,0] neg_hi:[1,0]
	v_pk_mul_f32 v[100:101], v[100:101], v[114:115] op_sel_hi:[1,0]
	v_pk_fma_f32 v[10:11], v[10:11], v[42:43], v[100:101]
	s_waitcnt lgkmcnt(8)
	v_pk_add_f32 v[102:103], v[44:45], 1.0 op_sel_hi:[1,0] neg_lo:[1,0] neg_hi:[1,0]
	v_pk_mul_f32 v[102:103], v[102:103], v[114:115] op_sel_hi:[1,0]
	v_pk_fma_f32 v[12:13], v[12:13], v[44:45], v[102:103]
	v_pk_add_f32 v[104:105], v[46:47], 1.0 op_sel_hi:[1,0] neg_lo:[1,0] neg_hi:[1,0]
	v_pk_mul_f32 v[104:105], v[104:105], v[114:115] op_sel_hi:[1,0]
	v_pk_fma_f32 v[14:15], v[14:15], v[46:47], v[104:105]
	ds_read_b128 v[82:85], v126 offset:6208
	ds_read_b128 v[86:89], v126 offset:6224
	ds_read_b128 v[90:93], v126 offset:6240
	ds_read_b128 v[94:97], v126 offset:6256
	s_waitcnt lgkmcnt(11)
	v_pk_add_f32 v[98:99], v[48:49], 1.0 op_sel_hi:[1,0] neg_lo:[1,0] neg_hi:[1,0]
	v_pk_mul_f32 v[98:99], v[98:99], v[114:115] op_sel_hi:[1,0]
	v_pk_fma_f32 v[16:17], v[16:17], v[48:49], v[98:99]
	v_pk_add_f32 v[100:101], v[50:51], 1.0 op_sel_hi:[1,0] neg_lo:[1,0] neg_hi:[1,0]
	v_pk_mul_f32 v[100:101], v[100:101], v[114:115] op_sel_hi:[1,0]
	v_pk_fma_f32 v[18:19], v[18:19], v[50:51], v[100:101]
	s_waitcnt lgkmcnt(10)
	v_pk_add_f32 v[102:103], v[52:53], 1.0 op_sel_hi:[1,0] neg_lo:[1,0] neg_hi:[1,0]
	v_pk_mul_f32 v[102:103], v[102:103], v[114:115] op_sel_hi:[1,0]
	v_pk_fma_f32 v[20:21], v[20:21], v[52:53], v[102:103]
	v_pk_add_f32 v[104:105], v[54:55], 1.0 op_sel_hi:[1,0] neg_lo:[1,0] neg_hi:[1,0]
	v_pk_mul_f32 v[104:105], v[104:105], v[114:115] op_sel_hi:[1,0]
	v_pk_fma_f32 v[22:23], v[22:23], v[54:55], v[104:105]
	s_waitcnt lgkmcnt(9)
	v_pk_add_f32 v[98:99], v[56:57], 1.0 op_sel_hi:[1,0] neg_lo:[1,0] neg_hi:[1,0]
	v_pk_mul_f32 v[98:99], v[98:99], v[114:115] op_sel_hi:[1,0]
	v_pk_fma_f32 v[24:25], v[24:25], v[56:57], v[98:99]
	v_pk_add_f32 v[100:101], v[58:59], 1.0 op_sel_hi:[1,0] neg_lo:[1,0] neg_hi:[1,0]
	v_pk_mul_f32 v[100:101], v[100:101], v[114:115] op_sel_hi:[1,0]
	v_pk_fma_f32 v[26:27], v[26:27], v[58:59], v[100:101]
	s_waitcnt lgkmcnt(8)
	v_pk_add_f32 v[102:103], v[60:61], 1.0 op_sel_hi:[1,0] neg_lo:[1,0] neg_hi:[1,0]
	v_pk_mul_f32 v[102:103], v[102:103], v[114:115] op_sel_hi:[1,0]
	v_pk_fma_f32 v[28:29], v[28:29], v[60:61], v[102:103]
	v_pk_add_f32 v[104:105], v[62:63], 1.0 op_sel_hi:[1,0] neg_lo:[1,0] neg_hi:[1,0]
	v_pk_mul_f32 v[104:105], v[104:105], v[114:115] op_sel_hi:[1,0]
	v_pk_fma_f32 v[30:31], v[30:31], v[62:63], v[104:105]
	s_waitcnt lgkmcnt(0)
	v_fma_f32 v128, v66, v0, 0
	v_fmac_f32_e32 v128, v67, v1
	v_fmac_f32_e32 v128, v68, v2
	v_fmac_f32_e32 v128, v69, v3
	v_fmac_f32_e32 v128, v70, v4
	v_fmac_f32_e32 v128, v71, v5
	v_fmac_f32_e32 v128, v72, v6
	v_fmac_f32_e32 v128, v73, v7
	v_fmac_f32_e32 v128, v74, v8
	v_fmac_f32_e32 v128, v75, v9
	v_fmac_f32_e32 v128, v76, v10
	v_fmac_f32_e32 v128, v77, v11
	v_fmac_f32_e32 v128, v78, v12
	v_fmac_f32_e32 v128, v79, v13
	v_fmac_f32_e32 v128, v80, v14
	v_fmac_f32_e32 v128, v81, v15
	v_fmac_f32_e32 v128, v82, v16
	v_fmac_f32_e32 v128, v83, v17
	v_fmac_f32_e32 v128, v84, v18
	v_fmac_f32_e32 v128, v85, v19
	v_fmac_f32_e32 v128, v86, v20
	v_fmac_f32_e32 v128, v87, v21
	v_fmac_f32_e32 v128, v88, v22
	v_fmac_f32_e32 v128, v89, v23
	v_fmac_f32_e32 v128, v90, v24
	v_fmac_f32_e32 v128, v91, v25
	v_fmac_f32_e32 v128, v92, v26
	v_fmac_f32_e32 v128, v93, v27
	v_fmac_f32_e32 v128, v94, v28
	v_fmac_f32_e32 v128, v95, v29
	v_fmac_f32_e32 v128, v96, v30
	v_fmac_f32_e32 v128, v97, v31
	ds_write_b32 v127, v128 offset:8192
	ds_read_b128 v[32:35], v126 offset:2560
	ds_read_b128 v[36:39], v126 offset:2576
	ds_read_b128 v[40:43], v126 offset:2592
	ds_read_b128 v[44:47], v126 offset:2608
	ds_read_b128 v[48:51], v126 offset:2624
	ds_read_b128 v[52:55], v126 offset:2640
	ds_read_b128 v[56:59], v126 offset:2656
	ds_read_b128 v[60:63], v126 offset:2672
	ds_read_b128 v[66:69], v126 offset:6656
	ds_read_b128 v[70:73], v126 offset:6672
	ds_read_b128 v[74:77], v126 offset:6688
	ds_read_b128 v[78:81], v126 offset:6704
	s_waitcnt lgkmcnt(11)
	v_pk_add_f32 v[98:99], v[32:33], 1.0 op_sel_hi:[1,0] neg_lo:[1,0] neg_hi:[1,0]
	v_pk_mul_f32 v[98:99], v[98:99], v[116:117] op_sel_hi:[1,0]
	v_pk_fma_f32 v[0:1], v[0:1], v[32:33], v[98:99]
	v_pk_add_f32 v[100:101], v[34:35], 1.0 op_sel_hi:[1,0] neg_lo:[1,0] neg_hi:[1,0]
	v_pk_mul_f32 v[100:101], v[100:101], v[116:117] op_sel_hi:[1,0]
	v_pk_fma_f32 v[2:3], v[2:3], v[34:35], v[100:101]
	s_waitcnt lgkmcnt(10)
	v_pk_add_f32 v[102:103], v[36:37], 1.0 op_sel_hi:[1,0] neg_lo:[1,0] neg_hi:[1,0]
	v_pk_mul_f32 v[102:103], v[102:103], v[116:117] op_sel_hi:[1,0]
	v_pk_fma_f32 v[4:5], v[4:5], v[36:37], v[102:103]
	v_pk_add_f32 v[104:105], v[38:39], 1.0 op_sel_hi:[1,0] neg_lo:[1,0] neg_hi:[1,0]
	v_pk_mul_f32 v[104:105], v[104:105], v[116:117] op_sel_hi:[1,0]
	v_pk_fma_f32 v[6:7], v[6:7], v[38:39], v[104:105]
	s_waitcnt lgkmcnt(9)
	v_pk_add_f32 v[98:99], v[40:41], 1.0 op_sel_hi:[1,0] neg_lo:[1,0] neg_hi:[1,0]
	v_pk_mul_f32 v[98:99], v[98:99], v[116:117] op_sel_hi:[1,0]
	v_pk_fma_f32 v[8:9], v[8:9], v[40:41], v[98:99]
	v_pk_add_f32 v[100:101], v[42:43], 1.0 op_sel_hi:[1,0] neg_lo:[1,0] neg_hi:[1,0]
	v_pk_mul_f32 v[100:101], v[100:101], v[116:117] op_sel_hi:[1,0]
	v_pk_fma_f32 v[10:11], v[10:11], v[42:43], v[100:101]
	s_waitcnt lgkmcnt(8)
	v_pk_add_f32 v[102:103], v[44:45], 1.0 op_sel_hi:[1,0] neg_lo:[1,0] neg_hi:[1,0]
	v_pk_mul_f32 v[102:103], v[102:103], v[116:117] op_sel_hi:[1,0]
	v_pk_fma_f32 v[12:13], v[12:13], v[44:45], v[102:103]
	v_pk_add_f32 v[104:105], v[46:47], 1.0 op_sel_hi:[1,0] neg_lo:[1,0] neg_hi:[1,0]
	v_pk_mul_f32 v[104:105], v[104:105], v[116:117] op_sel_hi:[1,0]
	v_pk_fma_f32 v[14:15], v[14:15], v[46:47], v[104:105]
	ds_read_b128 v[82:85], v126 offset:6720
	ds_read_b128 v[86:89], v126 offset:6736
	ds_read_b128 v[90:93], v126 offset:6752
	ds_read_b128 v[94:97], v126 offset:6768
	s_waitcnt lgkmcnt(11)
	v_pk_add_f32 v[98:99], v[48:49], 1.0 op_sel_hi:[1,0] neg_lo:[1,0] neg_hi:[1,0]
	v_pk_mul_f32 v[98:99], v[98:99], v[116:117] op_sel_hi:[1,0]
	v_pk_fma_f32 v[16:17], v[16:17], v[48:49], v[98:99]
	v_pk_add_f32 v[100:101], v[50:51], 1.0 op_sel_hi:[1,0] neg_lo:[1,0] neg_hi:[1,0]
	v_pk_mul_f32 v[100:101], v[100:101], v[116:117] op_sel_hi:[1,0]
	v_pk_fma_f32 v[18:19], v[18:19], v[50:51], v[100:101]
	s_waitcnt lgkmcnt(10)
	v_pk_add_f32 v[102:103], v[52:53], 1.0 op_sel_hi:[1,0] neg_lo:[1,0] neg_hi:[1,0]
	v_pk_mul_f32 v[102:103], v[102:103], v[116:117] op_sel_hi:[1,0]
	v_pk_fma_f32 v[20:21], v[20:21], v[52:53], v[102:103]
	v_pk_add_f32 v[104:105], v[54:55], 1.0 op_sel_hi:[1,0] neg_lo:[1,0] neg_hi:[1,0]
	v_pk_mul_f32 v[104:105], v[104:105], v[116:117] op_sel_hi:[1,0]
	v_pk_fma_f32 v[22:23], v[22:23], v[54:55], v[104:105]
	s_waitcnt lgkmcnt(9)
	v_pk_add_f32 v[98:99], v[56:57], 1.0 op_sel_hi:[1,0] neg_lo:[1,0] neg_hi:[1,0]
	v_pk_mul_f32 v[98:99], v[98:99], v[116:117] op_sel_hi:[1,0]
	v_pk_fma_f32 v[24:25], v[24:25], v[56:57], v[98:99]
	v_pk_add_f32 v[100:101], v[58:59], 1.0 op_sel_hi:[1,0] neg_lo:[1,0] neg_hi:[1,0]
	v_pk_mul_f32 v[100:101], v[100:101], v[116:117] op_sel_hi:[1,0]
	v_pk_fma_f32 v[26:27], v[26:27], v[58:59], v[100:101]
	s_waitcnt lgkmcnt(8)
	v_pk_add_f32 v[102:103], v[60:61], 1.0 op_sel_hi:[1,0] neg_lo:[1,0] neg_hi:[1,0]
	v_pk_mul_f32 v[102:103], v[102:103], v[116:117] op_sel_hi:[1,0]
	v_pk_fma_f32 v[28:29], v[28:29], v[60:61], v[102:103]
	v_pk_add_f32 v[104:105], v[62:63], 1.0 op_sel_hi:[1,0] neg_lo:[1,0] neg_hi:[1,0]
	v_pk_mul_f32 v[104:105], v[104:105], v[116:117] op_sel_hi:[1,0]
	v_pk_fma_f32 v[30:31], v[30:31], v[62:63], v[104:105]
	s_waitcnt lgkmcnt(0)
	v_fma_f32 v128, v66, v0, 0
	v_fmac_f32_e32 v128, v67, v1
	v_fmac_f32_e32 v128, v68, v2
	v_fmac_f32_e32 v128, v69, v3
	v_fmac_f32_e32 v128, v70, v4
	v_fmac_f32_e32 v128, v71, v5
	v_fmac_f32_e32 v128, v72, v6
	v_fmac_f32_e32 v128, v73, v7
	v_fmac_f32_e32 v128, v74, v8
	v_fmac_f32_e32 v128, v75, v9
	v_fmac_f32_e32 v128, v76, v10
	v_fmac_f32_e32 v128, v77, v11
	v_fmac_f32_e32 v128, v78, v12
	v_fmac_f32_e32 v128, v79, v13
	v_fmac_f32_e32 v128, v80, v14
	v_fmac_f32_e32 v128, v81, v15
	v_fmac_f32_e32 v128, v82, v16
	v_fmac_f32_e32 v128, v83, v17
	v_fmac_f32_e32 v128, v84, v18
	v_fmac_f32_e32 v128, v85, v19
	v_fmac_f32_e32 v128, v86, v20
	v_fmac_f32_e32 v128, v87, v21
	v_fmac_f32_e32 v128, v88, v22
	v_fmac_f32_e32 v128, v89, v23
	v_fmac_f32_e32 v128, v90, v24
	v_fmac_f32_e32 v128, v91, v25
	v_fmac_f32_e32 v128, v92, v26
	v_fmac_f32_e32 v128, v93, v27
	v_fmac_f32_e32 v128, v94, v28
	v_fmac_f32_e32 v128, v95, v29
	v_fmac_f32_e32 v128, v96, v30
	v_fmac_f32_e32 v128, v97, v31
	ds_write_b32 v127, v128 offset:10240
	ds_read_b128 v[32:35], v126 offset:3072
	ds_read_b128 v[36:39], v126 offset:3088
	ds_read_b128 v[40:43], v126 offset:3104
	ds_read_b128 v[44:47], v126 offset:3120
	ds_read_b128 v[48:51], v126 offset:3136
	ds_read_b128 v[52:55], v126 offset:3152
	ds_read_b128 v[56:59], v126 offset:3168
	ds_read_b128 v[60:63], v126 offset:3184
	ds_read_b128 v[66:69], v126 offset:7168
	ds_read_b128 v[70:73], v126 offset:7184
	ds_read_b128 v[74:77], v126 offset:7200
	ds_read_b128 v[78:81], v126 offset:7216
	s_waitcnt lgkmcnt(11)
	v_pk_add_f32 v[98:99], v[32:33], 1.0 op_sel_hi:[1,0] neg_lo:[1,0] neg_hi:[1,0]
	v_pk_mul_f32 v[98:99], v[98:99], v[118:119] op_sel_hi:[1,0]
	v_pk_fma_f32 v[0:1], v[0:1], v[32:33], v[98:99]
	v_pk_add_f32 v[100:101], v[34:35], 1.0 op_sel_hi:[1,0] neg_lo:[1,0] neg_hi:[1,0]
	v_pk_mul_f32 v[100:101], v[100:101], v[118:119] op_sel_hi:[1,0]
	v_pk_fma_f32 v[2:3], v[2:3], v[34:35], v[100:101]
	s_waitcnt lgkmcnt(10)
	v_pk_add_f32 v[102:103], v[36:37], 1.0 op_sel_hi:[1,0] neg_lo:[1,0] neg_hi:[1,0]
	v_pk_mul_f32 v[102:103], v[102:103], v[118:119] op_sel_hi:[1,0]
	v_pk_fma_f32 v[4:5], v[4:5], v[36:37], v[102:103]
	v_pk_add_f32 v[104:105], v[38:39], 1.0 op_sel_hi:[1,0] neg_lo:[1,0] neg_hi:[1,0]
	v_pk_mul_f32 v[104:105], v[104:105], v[118:119] op_sel_hi:[1,0]
	v_pk_fma_f32 v[6:7], v[6:7], v[38:39], v[104:105]
	s_waitcnt lgkmcnt(9)
	v_pk_add_f32 v[98:99], v[40:41], 1.0 op_sel_hi:[1,0] neg_lo:[1,0] neg_hi:[1,0]
	v_pk_mul_f32 v[98:99], v[98:99], v[118:119] op_sel_hi:[1,0]
	v_pk_fma_f32 v[8:9], v[8:9], v[40:41], v[98:99]
	v_pk_add_f32 v[100:101], v[42:43], 1.0 op_sel_hi:[1,0] neg_lo:[1,0] neg_hi:[1,0]
	v_pk_mul_f32 v[100:101], v[100:101], v[118:119] op_sel_hi:[1,0]
	v_pk_fma_f32 v[10:11], v[10:11], v[42:43], v[100:101]
	s_waitcnt lgkmcnt(8)
	v_pk_add_f32 v[102:103], v[44:45], 1.0 op_sel_hi:[1,0] neg_lo:[1,0] neg_hi:[1,0]
	v_pk_mul_f32 v[102:103], v[102:103], v[118:119] op_sel_hi:[1,0]
	v_pk_fma_f32 v[12:13], v[12:13], v[44:45], v[102:103]
	v_pk_add_f32 v[104:105], v[46:47], 1.0 op_sel_hi:[1,0] neg_lo:[1,0] neg_hi:[1,0]
	v_pk_mul_f32 v[104:105], v[104:105], v[118:119] op_sel_hi:[1,0]
	v_pk_fma_f32 v[14:15], v[14:15], v[46:47], v[104:105]
	ds_read_b128 v[82:85], v126 offset:7232
	ds_read_b128 v[86:89], v126 offset:7248
	ds_read_b128 v[90:93], v126 offset:7264
	ds_read_b128 v[94:97], v126 offset:7280
	s_waitcnt lgkmcnt(11)
	v_pk_add_f32 v[98:99], v[48:49], 1.0 op_sel_hi:[1,0] neg_lo:[1,0] neg_hi:[1,0]
	v_pk_mul_f32 v[98:99], v[98:99], v[118:119] op_sel_hi:[1,0]
	v_pk_fma_f32 v[16:17], v[16:17], v[48:49], v[98:99]
	v_pk_add_f32 v[100:101], v[50:51], 1.0 op_sel_hi:[1,0] neg_lo:[1,0] neg_hi:[1,0]
	v_pk_mul_f32 v[100:101], v[100:101], v[118:119] op_sel_hi:[1,0]
	v_pk_fma_f32 v[18:19], v[18:19], v[50:51], v[100:101]
	s_waitcnt lgkmcnt(10)
	v_pk_add_f32 v[102:103], v[52:53], 1.0 op_sel_hi:[1,0] neg_lo:[1,0] neg_hi:[1,0]
	v_pk_mul_f32 v[102:103], v[102:103], v[118:119] op_sel_hi:[1,0]
	v_pk_fma_f32 v[20:21], v[20:21], v[52:53], v[102:103]
	v_pk_add_f32 v[104:105], v[54:55], 1.0 op_sel_hi:[1,0] neg_lo:[1,0] neg_hi:[1,0]
	v_pk_mul_f32 v[104:105], v[104:105], v[118:119] op_sel_hi:[1,0]
	v_pk_fma_f32 v[22:23], v[22:23], v[54:55], v[104:105]
	s_waitcnt lgkmcnt(9)
	v_pk_add_f32 v[98:99], v[56:57], 1.0 op_sel_hi:[1,0] neg_lo:[1,0] neg_hi:[1,0]
	v_pk_mul_f32 v[98:99], v[98:99], v[118:119] op_sel_hi:[1,0]
	v_pk_fma_f32 v[24:25], v[24:25], v[56:57], v[98:99]
	v_pk_add_f32 v[100:101], v[58:59], 1.0 op_sel_hi:[1,0] neg_lo:[1,0] neg_hi:[1,0]
	v_pk_mul_f32 v[100:101], v[100:101], v[118:119] op_sel_hi:[1,0]
	v_pk_fma_f32 v[26:27], v[26:27], v[58:59], v[100:101]
	s_waitcnt lgkmcnt(8)
	v_pk_add_f32 v[102:103], v[60:61], 1.0 op_sel_hi:[1,0] neg_lo:[1,0] neg_hi:[1,0]
	v_pk_mul_f32 v[102:103], v[102:103], v[118:119] op_sel_hi:[1,0]
	v_pk_fma_f32 v[28:29], v[28:29], v[60:61], v[102:103]
	v_pk_add_f32 v[104:105], v[62:63], 1.0 op_sel_hi:[1,0] neg_lo:[1,0] neg_hi:[1,0]
	v_pk_mul_f32 v[104:105], v[104:105], v[118:119] op_sel_hi:[1,0]
	v_pk_fma_f32 v[30:31], v[30:31], v[62:63], v[104:105]
	s_waitcnt lgkmcnt(0)
	v_fma_f32 v128, v66, v0, 0
	v_fmac_f32_e32 v128, v67, v1
	v_fmac_f32_e32 v128, v68, v2
	v_fmac_f32_e32 v128, v69, v3
	v_fmac_f32_e32 v128, v70, v4
	v_fmac_f32_e32 v128, v71, v5
	v_fmac_f32_e32 v128, v72, v6
	v_fmac_f32_e32 v128, v73, v7
	v_fmac_f32_e32 v128, v74, v8
	v_fmac_f32_e32 v128, v75, v9
	v_fmac_f32_e32 v128, v76, v10
	v_fmac_f32_e32 v128, v77, v11
	v_fmac_f32_e32 v128, v78, v12
	v_fmac_f32_e32 v128, v79, v13
	v_fmac_f32_e32 v128, v80, v14
	v_fmac_f32_e32 v128, v81, v15
	v_fmac_f32_e32 v128, v82, v16
	v_fmac_f32_e32 v128, v83, v17
	v_fmac_f32_e32 v128, v84, v18
	v_fmac_f32_e32 v128, v85, v19
	v_fmac_f32_e32 v128, v86, v20
	v_fmac_f32_e32 v128, v87, v21
	v_fmac_f32_e32 v128, v88, v22
	v_fmac_f32_e32 v128, v89, v23
	v_fmac_f32_e32 v128, v90, v24
	v_fmac_f32_e32 v128, v91, v25
	v_fmac_f32_e32 v128, v92, v26
	v_fmac_f32_e32 v128, v93, v27
	v_fmac_f32_e32 v128, v94, v28
	v_fmac_f32_e32 v128, v95, v29
	v_fmac_f32_e32 v128, v96, v30
	v_fmac_f32_e32 v128, v97, v31
	ds_write_b32 v127, v128 offset:12288
	ds_read_b128 v[32:35], v126 offset:3584
	ds_read_b128 v[36:39], v126 offset:3600
	ds_read_b128 v[40:43], v126 offset:3616
	ds_read_b128 v[44:47], v126 offset:3632
	ds_read_b128 v[48:51], v126 offset:3648
	ds_read_b128 v[52:55], v126 offset:3664
	ds_read_b128 v[56:59], v126 offset:3680
	ds_read_b128 v[60:63], v126 offset:3696
	ds_read_b128 v[66:69], v126 offset:7680
	ds_read_b128 v[70:73], v126 offset:7696
	ds_read_b128 v[74:77], v126 offset:7712
	ds_read_b128 v[78:81], v126 offset:7728
	s_waitcnt lgkmcnt(11)
	v_pk_add_f32 v[98:99], v[32:33], 1.0 op_sel_hi:[1,0] neg_lo:[1,0] neg_hi:[1,0]
	v_pk_mul_f32 v[98:99], v[98:99], v[120:121] op_sel_hi:[1,0]
	v_pk_fma_f32 v[0:1], v[0:1], v[32:33], v[98:99]
	v_pk_add_f32 v[100:101], v[34:35], 1.0 op_sel_hi:[1,0] neg_lo:[1,0] neg_hi:[1,0]
	v_pk_mul_f32 v[100:101], v[100:101], v[120:121] op_sel_hi:[1,0]
	v_pk_fma_f32 v[2:3], v[2:3], v[34:35], v[100:101]
	s_waitcnt lgkmcnt(10)
	v_pk_add_f32 v[102:103], v[36:37], 1.0 op_sel_hi:[1,0] neg_lo:[1,0] neg_hi:[1,0]
	v_pk_mul_f32 v[102:103], v[102:103], v[120:121] op_sel_hi:[1,0]
	v_pk_fma_f32 v[4:5], v[4:5], v[36:37], v[102:103]
	v_pk_add_f32 v[104:105], v[38:39], 1.0 op_sel_hi:[1,0] neg_lo:[1,0] neg_hi:[1,0]
	v_pk_mul_f32 v[104:105], v[104:105], v[120:121] op_sel_hi:[1,0]
	v_pk_fma_f32 v[6:7], v[6:7], v[38:39], v[104:105]
	s_waitcnt lgkmcnt(9)
	v_pk_add_f32 v[98:99], v[40:41], 1.0 op_sel_hi:[1,0] neg_lo:[1,0] neg_hi:[1,0]
	v_pk_mul_f32 v[98:99], v[98:99], v[120:121] op_sel_hi:[1,0]
	v_pk_fma_f32 v[8:9], v[8:9], v[40:41], v[98:99]
	v_pk_add_f32 v[100:101], v[42:43], 1.0 op_sel_hi:[1,0] neg_lo:[1,0] neg_hi:[1,0]
	v_pk_mul_f32 v[100:101], v[100:101], v[120:121] op_sel_hi:[1,0]
	v_pk_fma_f32 v[10:11], v[10:11], v[42:43], v[100:101]
	s_waitcnt lgkmcnt(8)
	v_pk_add_f32 v[102:103], v[44:45], 1.0 op_sel_hi:[1,0] neg_lo:[1,0] neg_hi:[1,0]
	v_pk_mul_f32 v[102:103], v[102:103], v[120:121] op_sel_hi:[1,0]
	v_pk_fma_f32 v[12:13], v[12:13], v[44:45], v[102:103]
	v_pk_add_f32 v[104:105], v[46:47], 1.0 op_sel_hi:[1,0] neg_lo:[1,0] neg_hi:[1,0]
	v_pk_mul_f32 v[104:105], v[104:105], v[120:121] op_sel_hi:[1,0]
	v_pk_fma_f32 v[14:15], v[14:15], v[46:47], v[104:105]
	ds_read_b128 v[82:85], v126 offset:7744
	ds_read_b128 v[86:89], v126 offset:7760
	ds_read_b128 v[90:93], v126 offset:7776
	ds_read_b128 v[94:97], v126 offset:7792
	s_waitcnt lgkmcnt(11)
	v_pk_add_f32 v[98:99], v[48:49], 1.0 op_sel_hi:[1,0] neg_lo:[1,0] neg_hi:[1,0]
	v_pk_mul_f32 v[98:99], v[98:99], v[120:121] op_sel_hi:[1,0]
	v_pk_fma_f32 v[16:17], v[16:17], v[48:49], v[98:99]
	v_pk_add_f32 v[100:101], v[50:51], 1.0 op_sel_hi:[1,0] neg_lo:[1,0] neg_hi:[1,0]
	v_pk_mul_f32 v[100:101], v[100:101], v[120:121] op_sel_hi:[1,0]
	v_pk_fma_f32 v[18:19], v[18:19], v[50:51], v[100:101]
	s_waitcnt lgkmcnt(10)
	v_pk_add_f32 v[102:103], v[52:53], 1.0 op_sel_hi:[1,0] neg_lo:[1,0] neg_hi:[1,0]
	v_pk_mul_f32 v[102:103], v[102:103], v[120:121] op_sel_hi:[1,0]
	v_pk_fma_f32 v[20:21], v[20:21], v[52:53], v[102:103]
	v_pk_add_f32 v[104:105], v[54:55], 1.0 op_sel_hi:[1,0] neg_lo:[1,0] neg_hi:[1,0]
	v_pk_mul_f32 v[104:105], v[104:105], v[120:121] op_sel_hi:[1,0]
	v_pk_fma_f32 v[22:23], v[22:23], v[54:55], v[104:105]
	s_waitcnt lgkmcnt(9)
	v_pk_add_f32 v[98:99], v[56:57], 1.0 op_sel_hi:[1,0] neg_lo:[1,0] neg_hi:[1,0]
	v_pk_mul_f32 v[98:99], v[98:99], v[120:121] op_sel_hi:[1,0]
	v_pk_fma_f32 v[24:25], v[24:25], v[56:57], v[98:99]
	v_pk_add_f32 v[100:101], v[58:59], 1.0 op_sel_hi:[1,0] neg_lo:[1,0] neg_hi:[1,0]
	v_pk_mul_f32 v[100:101], v[100:101], v[120:121] op_sel_hi:[1,0]
	v_pk_fma_f32 v[26:27], v[26:27], v[58:59], v[100:101]
	s_waitcnt lgkmcnt(8)
	v_pk_add_f32 v[102:103], v[60:61], 1.0 op_sel_hi:[1,0] neg_lo:[1,0] neg_hi:[1,0]
	v_pk_mul_f32 v[102:103], v[102:103], v[120:121] op_sel_hi:[1,0]
	v_pk_fma_f32 v[28:29], v[28:29], v[60:61], v[102:103]
	v_pk_add_f32 v[104:105], v[62:63], 1.0 op_sel_hi:[1,0] neg_lo:[1,0] neg_hi:[1,0]
	v_pk_mul_f32 v[104:105], v[104:105], v[120:121] op_sel_hi:[1,0]
	v_pk_fma_f32 v[30:31], v[30:31], v[62:63], v[104:105]
	s_waitcnt lgkmcnt(0)
	v_fma_f32 v128, v66, v0, 0
	v_fmac_f32_e32 v128, v67, v1
	v_fmac_f32_e32 v128, v68, v2
	v_fmac_f32_e32 v128, v69, v3
	v_fmac_f32_e32 v128, v70, v4
	v_fmac_f32_e32 v128, v71, v5
	v_fmac_f32_e32 v128, v72, v6
	v_fmac_f32_e32 v128, v73, v7
	v_fmac_f32_e32 v128, v74, v8
	v_fmac_f32_e32 v128, v75, v9
	v_fmac_f32_e32 v128, v76, v10
	v_fmac_f32_e32 v128, v77, v11
	v_fmac_f32_e32 v128, v78, v12
	v_fmac_f32_e32 v128, v79, v13
	v_fmac_f32_e32 v128, v80, v14
	v_fmac_f32_e32 v128, v81, v15
	v_fmac_f32_e32 v128, v82, v16
	v_fmac_f32_e32 v128, v83, v17
	v_fmac_f32_e32 v128, v84, v18
	v_fmac_f32_e32 v128, v85, v19
	v_fmac_f32_e32 v128, v86, v20
	v_fmac_f32_e32 v128, v87, v21
	v_fmac_f32_e32 v128, v88, v22
	v_fmac_f32_e32 v128, v89, v23
	v_fmac_f32_e32 v128, v90, v24
	v_fmac_f32_e32 v128, v91, v25
	v_fmac_f32_e32 v128, v92, v26
	v_fmac_f32_e32 v128, v93, v27
	v_fmac_f32_e32 v128, v94, v28
	v_fmac_f32_e32 v128, v95, v29
	v_fmac_f32_e32 v128, v96, v30
	v_fmac_f32_e32 v128, v97, v31
	ds_write_b32 v127, v128 offset:14336
	s_add_u32 s16, s88, 0x8600000
	s_addc_u32 s17, s89, 0
	s_add_u32 s16, s16, s14
	s_addc_u32 s17, s17, 0
	global_store_dword v123, v0, s[16:17]
	global_store_dword v123, v1, s[16:17] offset:512
	global_store_dword v123, v2, s[16:17] offset:1024
	global_store_dword v123, v3, s[16:17] offset:1536
	global_store_dword v123, v4, s[16:17] offset:2048
	global_store_dword v123, v5, s[16:17] offset:2560
	global_store_dword v123, v6, s[16:17] offset:3072
	global_store_dword v123, v7, s[16:17] offset:3584
	s_add_u32 s16, s16, 0x1000
	s_addc_u32 s17, s17, 0
	global_store_dword v123, v8, s[16:17]
	global_store_dword v123, v9, s[16:17] offset:512
	global_store_dword v123, v10, s[16:17] offset:1024
	global_store_dword v123, v11, s[16:17] offset:1536
	global_store_dword v123, v12, s[16:17] offset:2048
	global_store_dword v123, v13, s[16:17] offset:2560
	global_store_dword v123, v14, s[16:17] offset:3072
	global_store_dword v123, v15, s[16:17] offset:3584
	s_add_u32 s16, s16, 0x1000
	s_addc_u32 s17, s17, 0
	global_store_dword v123, v16, s[16:17]
	global_store_dword v123, v17, s[16:17] offset:512
	global_store_dword v123, v18, s[16:17] offset:1024
	global_store_dword v123, v19, s[16:17] offset:1536
	global_store_dword v123, v20, s[16:17] offset:2048
	global_store_dword v123, v21, s[16:17] offset:2560
	global_store_dword v123, v22, s[16:17] offset:3072
	global_store_dword v123, v23, s[16:17] offset:3584
	s_add_u32 s16, s16, 0x1000
	s_addc_u32 s17, s17, 0
	global_store_dword v123, v24, s[16:17]
	global_store_dword v123, v25, s[16:17] offset:512
	global_store_dword v123, v26, s[16:17] offset:1024
	global_store_dword v123, v27, s[16:17] offset:1536
	global_store_dword v123, v28, s[16:17] offset:2048
	global_store_dword v123, v29, s[16:17] offset:2560
	global_store_dword v123, v30, s[16:17] offset:3072
	global_store_dword v123, v31, s[16:17] offset:3584
	s_waitcnt lgkmcnt(0)
	s_barrier
	v_lshrrev_b32_e32 v98, 7, v64
	v_lshlrev_b32_e32 v99, 11, v98
	v_lshl_add_u32 v99, v129, 2, v99
	v_add_u32_e32 v99, 0x2000, v99
	ds_read_b32 v100, v99
	ds_read_b32 v101, v99 offset:512
	ds_read_b32 v102, v99 offset:1024
	ds_read_b32 v103, v99 offset:1536
	ds_read_b32 v104, v99 offset:8192
	ds_read_b32 v122, v99 offset:8704
	ds_read_b32 v124, v99 offset:9216
	ds_read_b32 v125, v99 offset:9728
	s_lshl_b32 s2, s6, 12
	s_lshl_b32 s3, s8, 9
	s_add_u32 s2, s2, s3
	v_lshlrev_b32_e32 v126, 12, v98
	v_lshl_add_u32 v126, v129, 2, v126
	v_add_u32_e32 v126, s2, v126
	s_add_u32 s10, s90, 0xf12b600
	s_addc_u32 s11, s91, 0
	s_waitcnt lgkmcnt(4)
	v_add_f32_e32 v100, v100, v101
	v_add_f32_e32 v100, v100, v102
	v_add_f32_e32 v100, v100, v103
	global_store_dword v126, v100, s[10:11]
	s_waitcnt lgkmcnt(0)
	v_add_f32_e32 v104, v104, v122
	v_add_f32_e32 v104, v104, v124
	v_add_f32_e32 v104, v104, v125
	v_add_u32_e32 v126, 0x4000, v126
	global_store_dword v126, v104, s[10:11]
	s_mov_b64 s[0:1], exec

.LBB0_952:
	s_ashr_i32 s60, s54, 9
	s_ashr_i32 s61, s60, 31
	s_lshl_b32 s55, s54, 6
	s_lshl_b64 s[60:61], s[60:61], 12
	s_and_b32 s55, s55, 0xfc0
	s_or_b32 s60, s60, s55
	v_readfirstlane_b32 s55, v64
	s_ashr_i32 s76, s55, 6
	s_lshl_b32 s55, s76, 3
	s_ashr_i32 s65, s55, 31
	s_add_u32 s64, s60, s55
	s_addc_u32 s65, s61, s65
	s_lshl_b32 s77, s54, 1
	s_and_b32 s77, s77, 0x380
	v_or_b32_e32 v0, s77, v68
	v_mov_b32_e32 v1, v71
	s_mul_i32 s82, s65, 0x440
	v_mad_u64_u32 v[0:1], s[80:81], s64, v81, v[0:1]
	s_mov_b64 s[58:59], s[40:41]
	s_mov_b64 s[62:63], s[50:51]
	s_mov_b64 s[36:37], s[52:53]
	s_mov_b64 s[66:67], s[2:3]
	s_mov_b64 s[56:57], s[44:45]
	s_mov_b64 s[38:39], s[46:47]
	s_mov_b64 s[78:79], s[48:49]
	v_add_u32_e32 v1, s82, v1
	s_cmp_gt_i32 s76, 0
	v_lshl_add_u64 v[12:13], v[0:1], 2, s[78:79]
	flat_load_dwordx2 v[20:21], v[12:13]
	v_add_co_u32_e32 v2, vcc, s68, v12
	v_lshlrev_b64 v[0:1], 1, v[0:1]
	s_nop 0
	v_addc_co_u32_e32 v3, vcc, 0, v13, vcc
	v_lshl_add_u64 v[16:17], s[38:39], 0, v[0:1]
	v_add_co_u32_e32 v4, vcc, s69, v12
	v_lshl_add_u64 v[0:1], s[36:37], 0, v[0:1]
	flat_load_dword v49, v[16:17]
	flat_load_dword v48, v[16:17] offset:2176
	flat_load_dword v34, v[0:1]
	flat_load_dword v35, v[0:1] offset:2176
	v_addc_co_u32_e32 v5, vcc, 0, v13, vcc
	flat_load_dwordx2 v[14:15], v[2:3] offset:256
	flat_load_dwordx2 v[10:11], v[4:5] offset:512
	v_add_co_u32_e32 v2, vcc, s68, v16
	s_movk_i32 s36, 0x4000
	s_nop 0
	v_addc_co_u32_e32 v3, vcc, 0, v17, vcc
	v_add_co_u32_e32 v4, vcc, s68, v0
	s_nop 1
	v_addc_co_u32_e32 v5, vcc, 0, v1, vcc
	v_add_co_u32_e32 v6, vcc, s70, v12
	flat_load_dword v47, v[2:3] offset:256
	flat_load_dword v46, v[2:3] offset:2432
	flat_load_dword v36, v[4:5] offset:256
	flat_load_dword v37, v[4:5] offset:2432
	v_addc_co_u32_e32 v7, vcc, 0, v13, vcc
	v_add_co_u32_e32 v2, vcc, s36, v12
	s_movk_i32 s36, 0x5000
	s_nop 0
	v_addc_co_u32_e32 v3, vcc, 0, v13, vcc
	flat_load_dwordx2 v[8:9], v[6:7] offset:768
	s_nop 0
	flat_load_dwordx2 v[6:7], v[2:3] offset:1024
	v_add_co_u32_e32 v2, vcc, s69, v16
	s_nop 1
	v_addc_co_u32_e32 v3, vcc, 0, v17, vcc
	v_add_co_u32_e32 v4, vcc, s69, v0
	s_nop 1
	v_addc_co_u32_e32 v5, vcc, 0, v1, vcc
	v_add_co_u32_e32 v18, vcc, s36, v12
	s_movk_i32 s36, 0x6000
	s_nop 0
	v_addc_co_u32_e32 v19, vcc, 0, v13, vcc
	flat_load_dword v45, v[2:3] offset:512
	flat_load_dword v44, v[2:3] offset:2688
	flat_load_dword v38, v[4:5] offset:512
	flat_load_dword v39, v[4:5] offset:2688
	v_add_co_u32_e32 v2, vcc, s36, v12
	s_movk_i32 s36, 0x7000
	s_nop 0
	v_addc_co_u32_e32 v3, vcc, 0, v13, vcc
	flat_load_dwordx2 v[4:5], v[18:19] offset:1280
	s_nop 0
	flat_load_dwordx2 v[2:3], v[2:3] offset:1536
	v_add_co_u32_e32 v16, vcc, s70, v16
	s_nop 1
	v_addc_co_u32_e32 v17, vcc, 0, v17, vcc
	v_add_co_u32_e32 v18, vcc, s70, v0
	s_nop 1
	v_addc_co_u32_e32 v19, vcc, 0, v1, vcc
	v_add_co_u32_e32 v0, vcc, s36, v12
	s_nop 1
	v_addc_co_u32_e32 v1, vcc, 0, v13, vcc
	flat_load_dwordx2 v[0:1], v[0:1] offset:1792
	flat_load_dword v43, v[16:17] offset:768
	flat_load_dword v42, v[16:17] offset:2944
	flat_load_dword v40, v[18:19] offset:768
	flat_load_dword v41, v[18:19] offset:2944
	s_waitcnt vmcnt(0) lgkmcnt(0)
	v_cmp_gt_f32_e64 s[36:37], s71, v21
	v_cmp_gt_f32_e32 vcc, s71, v20
	s_nop 1
	v_cndmask_b32_e64 v12, 0, 32, vcc
	v_ldexp_f32 v12, v20, v12
	v_log_f32_e32 v12, v12
	v_cndmask_b32_e64 v16, 0, 32, s[36:37]
	v_ldexp_f32 v16, v21, v16
	v_log_f32_e32 v16, v16
	v_mul_f32_e32 v13, 0x3f317217, v12
	v_fma_f32 v13, v12, s72, -v13
	v_fmac_f32_e32 v13, 0x3377d1cf, v12
	v_fmac_f32_e32 v13, 0x3f317217, v12
	v_cmp_lt_f32_e64 s[38:39], |v12|, s73
	s_nop 1
	v_cndmask_b32_e64 v12, v12, v13, s[38:39]
	v_cndmask_b32_e32 v13, 0, v82, vcc
	v_cmp_gt_f32_e32 vcc, s71, v14
	v_sub_f32_e32 v12, v12, v13
	v_mul_f32_e32 v13, 0x3f317217, v16
	v_cndmask_b32_e64 v17, 0, 32, vcc
	v_fma_f32 v13, v16, s72, -v13
	v_ldexp_f32 v17, v14, v17
	v_fmac_f32_e32 v13, 0x3377d1cf, v16
	v_log_f32_e32 v17, v17
	v_fmac_f32_e32 v13, 0x3f317217, v16
	v_cmp_lt_f32_e64 s[38:39], |v16|, s73
	s_nop 1
	v_cndmask_b32_e64 v13, v16, v13, s[38:39]
	v_cndmask_b32_e64 v16, 0, v82, s[36:37]
	v_cmp_gt_f32_e64 s[36:37], s71, v15
	v_sub_f32_e32 v13, v13, v16
	v_mul_f32_e32 v16, 0x3f317217, v17
	v_cndmask_b32_e64 v18, 0, 32, s[36:37]
	v_ldexp_f32 v18, v15, v18
	v_fma_f32 v16, v17, s72, -v16
	v_log_f32_e32 v18, v18
	v_fmac_f32_e32 v16, 0x3377d1cf, v17
	v_fmac_f32_e32 v16, 0x3f317217, v17
	v_cmp_lt_f32_e64 s[38:39], |v17|, s73
	v_pk_add_f32 v[62:63], v[12:13], 0 op_sel_hi:[1,0]
	v_lshl_add_u32 v12, s76, 9, v65
	v_cndmask_b32_e64 v16, v17, v16, s[38:39]
	v_cndmask_b32_e32 v17, 0, v82, vcc
	v_cmp_gt_f32_e32 vcc, s71, v10
	v_sub_f32_e32 v16, v16, v17
	v_mul_f32_e32 v17, 0x3f317217, v18
	v_cndmask_b32_e64 v19, 0, 32, vcc
	v_fma_f32 v17, v18, s72, -v17
	v_ldexp_f32 v19, v10, v19
	v_fmac_f32_e32 v17, 0x3377d1cf, v18
	v_log_f32_e32 v19, v19
	v_fmac_f32_e32 v17, 0x3f317217, v18
	v_cmp_lt_f32_e64 s[38:39], |v18|, s73
	v_pk_add_f32 v[14:15], v[14:15], 1.0 op_sel_hi:[1,0] neg_lo:[1,0] neg_hi:[1,0]
	s_nop 0
	v_cndmask_b32_e64 v17, v18, v17, s[38:39]
	v_cndmask_b32_e64 v18, 0, v82, s[36:37]
	v_cmp_gt_f32_e64 s[36:37], s71, v11
	v_sub_f32_e32 v17, v17, v18
	v_mul_f32_e32 v18, 0x3f317217, v19
	v_cndmask_b32_e64 v22, 0, 32, s[36:37]
	v_ldexp_f32 v22, v11, v22
	v_fma_f32 v18, v19, s72, -v18
	v_log_f32_e32 v22, v22
	v_fmac_f32_e32 v18, 0x3377d1cf, v19
	v_fmac_f32_e32 v18, 0x3f317217, v19
	v_cmp_lt_f32_e64 s[38:39], |v19|, s73
	v_pk_add_f32 v[88:89], v[62:63], v[16:17]
	s_nop 0
	v_cndmask_b32_e64 v18, v19, v18, s[38:39]
	v_cndmask_b32_e32 v19, 0, v82, vcc
	v_cmp_gt_f32_e32 vcc, s71, v8
	v_sub_f32_e32 v18, v18, v19
	v_mul_f32_e32 v19, 0x3f317217, v22
	v_cndmask_b32_e64 v23, 0, 32, vcc
	v_fma_f32 v19, v22, s72, -v19
	v_ldexp_f32 v23, v8, v23
	v_fmac_f32_e32 v19, 0x3377d1cf, v22
	v_log_f32_e32 v23, v23
	v_fmac_f32_e32 v19, 0x3f317217, v22
	v_cmp_lt_f32_e64 s[38:39], |v22|, s73
	s_nop 1
	v_cndmask_b32_e64 v19, v22, v19, s[38:39]
	v_cndmask_b32_e64 v22, 0, v82, s[36:37]
	v_cmp_gt_f32_e64 s[36:37], s71, v9
	v_sub_f32_e32 v19, v19, v22
	v_mul_f32_e32 v22, 0x3f317217, v23
	v_cndmask_b32_e64 v24, 0, 32, s[36:37]
	v_ldexp_f32 v24, v9, v24
	v_fma_f32 v22, v23, s72, -v22
	v_log_f32_e32 v24, v24
	v_fmac_f32_e32 v22, 0x3377d1cf, v23
	v_fmac_f32_e32 v22, 0x3f317217, v23
	v_cmp_lt_f32_e64 s[38:39], |v23|, s73
	v_pk_add_f32 v[32:33], v[88:89], v[18:19]
	v_pk_add_f32 v[8:9], v[8:9], 1.0 op_sel_hi:[1,0] neg_lo:[1,0] neg_hi:[1,0]
	v_cndmask_b32_e64 v22, v23, v22, s[38:39]
	v_cndmask_b32_e32 v23, 0, v82, vcc
	v_cmp_gt_f32_e32 vcc, s71, v6
	v_sub_f32_e32 v22, v22, v23
	v_mul_f32_e32 v23, 0x3f317217, v24
	v_cndmask_b32_e64 v25, 0, 32, vcc
	v_fma_f32 v23, v24, s72, -v23
	v_ldexp_f32 v25, v6, v25
	v_fmac_f32_e32 v23, 0x3377d1cf, v24
	v_log_f32_e32 v25, v25
	v_fmac_f32_e32 v23, 0x3f317217, v24
	v_cmp_lt_f32_e64 s[38:39], |v24|, s73
	s_nop 1
	v_cndmask_b32_e64 v23, v24, v23, s[38:39]
	v_cndmask_b32_e64 v24, 0, v82, s[36:37]
	v_cmp_gt_f32_e64 s[36:37], s71, v7
	v_sub_f32_e32 v23, v23, v24
	v_mul_f32_e32 v24, 0x3f317217, v25
	v_cndmask_b32_e64 v26, 0, 32, s[36:37]
	v_ldexp_f32 v26, v7, v26
	v_fma_f32 v24, v25, s72, -v24
	v_log_f32_e32 v26, v26
	v_fmac_f32_e32 v24, 0x3377d1cf, v25
	v_fmac_f32_e32 v24, 0x3f317217, v25
	v_cmp_lt_f32_e64 s[38:39], |v25|, s73
	v_pk_add_f32 v[6:7], v[6:7], 1.0 op_sel_hi:[1,0] neg_lo:[1,0] neg_hi:[1,0]
	s_nop 0
	v_cndmask_b32_e64 v24, v25, v24, s[38:39]
	v_cndmask_b32_e32 v25, 0, v82, vcc
	v_cmp_gt_f32_e32 vcc, s71, v4
	v_sub_f32_e32 v24, v24, v25
	v_mul_f32_e32 v25, 0x3f317217, v26
	v_cndmask_b32_e64 v27, 0, 32, vcc
	v_fma_f32 v25, v26, s72, -v25
	v_ldexp_f32 v27, v4, v27
	v_fmac_f32_e32 v25, 0x3377d1cf, v26
	v_log_f32_e32 v27, v27
	v_fmac_f32_e32 v25, 0x3f317217, v26
	v_cmp_lt_f32_e64 s[38:39], |v26|, s73
	s_nop 1
	v_cndmask_b32_e64 v25, v26, v25, s[38:39]
	v_cndmask_b32_e64 v26, 0, v82, s[36:37]
	v_cmp_gt_f32_e64 s[36:37], s71, v5
	v_sub_f32_e32 v25, v25, v26
	v_mul_f32_e32 v26, 0x3f317217, v27
	v_cndmask_b32_e64 v28, 0, 32, s[36:37]
	v_ldexp_f32 v28, v5, v28
	v_fma_f32 v26, v27, s72, -v26
	v_log_f32_e32 v28, v28
	v_fmac_f32_e32 v26, 0x3377d1cf, v27
	v_fmac_f32_e32 v26, 0x3f317217, v27
	v_cmp_lt_f32_e64 s[38:39], |v27|, s73
	v_pk_add_f32 v[4:5], v[4:5], 1.0 op_sel_hi:[1,0] neg_lo:[1,0] neg_hi:[1,0]
	s_nop 0
	v_cndmask_b32_e64 v26, v27, v26, s[38:39]
	v_cndmask_b32_e32 v27, 0, v82, vcc
	v_cmp_gt_f32_e32 vcc, s71, v2
	v_sub_f32_e32 v26, v26, v27
	v_mul_f32_e32 v27, 0x3f317217, v28
	v_cndmask_b32_e64 v29, 0, 32, vcc
	v_fma_f32 v27, v28, s72, -v27
	v_ldexp_f32 v29, v2, v29
	v_fmac_f32_e32 v27, 0x3377d1cf, v28
	v_log_f32_e32 v29, v29
	v_fmac_f32_e32 v27, 0x3f317217, v28
	v_cmp_lt_f32_e64 s[38:39], |v28|, s73
	s_nop 1
	v_cndmask_b32_e64 v27, v28, v27, s[38:39]
	v_cndmask_b32_e64 v28, 0, v82, s[36:37]
	v_cmp_gt_f32_e64 s[36:37], s71, v3
	v_sub_f32_e32 v27, v27, v28
	v_mul_f32_e32 v28, 0x3f317217, v29
	v_cndmask_b32_e64 v30, 0, 32, s[36:37]
	v_ldexp_f32 v30, v3, v30
	v_fma_f32 v28, v29, s72, -v28
	v_log_f32_e32 v30, v30
	v_fmac_f32_e32 v28, 0x3377d1cf, v29
	v_fmac_f32_e32 v28, 0x3f317217, v29
	v_cmp_lt_f32_e64 s[38:39], |v29|, s73
	v_pk_add_f32 v[2:3], v[2:3], 1.0 op_sel_hi:[1,0] neg_lo:[1,0] neg_hi:[1,0]
	s_nop 0
	v_cndmask_b32_e64 v28, v29, v28, s[38:39]
	v_cndmask_b32_e32 v29, 0, v82, vcc
	s_waitcnt vmcnt(0) lgkmcnt(0)
	v_cmp_gt_f32_e32 vcc, s71, v0
	v_sub_f32_e32 v50, v28, v29
	v_mul_f32_e32 v28, 0x3f317217, v30
	v_cndmask_b32_e64 v29, 0, 32, vcc
	v_fma_f32 v28, v30, s72, -v28
	v_ldexp_f32 v29, v0, v29
	v_fmac_f32_e32 v28, 0x3377d1cf, v30
	v_log_f32_e32 v29, v29
	v_fmac_f32_e32 v28, 0x3f317217, v30
	v_cmp_lt_f32_e64 s[38:39], |v30|, s73
	s_nop 1
	v_cndmask_b32_e64 v28, v30, v28, s[38:39]
	v_cndmask_b32_e64 v30, 0, v82, s[36:37]
	v_cmp_gt_f32_e64 s[36:37], s71, v1
	v_sub_f32_e32 v51, v28, v30
	v_mul_f32_e32 v28, 0x3f317217, v29
	v_cndmask_b32_e64 v30, 0, 32, s[36:37]
	v_ldexp_f32 v30, v1, v30
	v_fma_f32 v28, v29, s72, -v28
	v_log_f32_e32 v30, v30
	v_fmac_f32_e32 v28, 0x3377d1cf, v29
	v_fmac_f32_e32 v28, 0x3f317217, v29
	v_cmp_lt_f32_e64 s[38:39], |v29|, s73
	v_pk_add_f32 v[0:1], v[0:1], 1.0 op_sel_hi:[1,0] neg_lo:[1,0] neg_hi:[1,0]
	s_nop 0
	v_cndmask_b32_e64 v28, v29, v28, s[38:39]
	v_cndmask_b32_e32 v29, 0, v82, vcc
	v_sub_f32_e32 v52, v28, v29
	v_mul_f32_e32 v28, 0x3f317217, v30
	v_fma_f32 v28, v30, s72, -v28
	v_fmac_f32_e32 v28, 0x3377d1cf, v30
	v_fmac_f32_e32 v28, 0x3f317217, v30
	v_cmp_lt_f32_e64 vcc, |v30|, s73
	v_cndmask_b32_e64 v29, 0, v82, s[36:37]
	s_nop 0
	v_cndmask_b32_e32 v28, v30, v28, vcc
	v_pk_add_f32 v[30:31], v[32:33], v[22:23]
	v_sub_f32_e32 v53, v28, v29
	v_pk_add_f32 v[28:29], v[30:31], v[24:25]
	s_cselect_b64 vcc, -1, 0
	v_pk_add_f32 v[26:27], v[28:29], v[26:27]
	s_cmp_gt_i32 s76, 1
	v_pk_add_f32 v[22:23], v[26:27], v[50:51]
	s_nop 0
	v_pk_add_f32 v[18:19], v[22:23], v[52:53]
	ds_write_b64 v12, v[18:19]
	s_waitcnt lgkmcnt(0)
	s_barrier
	ds_read2st64_b64 v[50:53], v65 offset1:1
	ds_read2st64_b64 v[54:57], v65 offset0:2 offset1:3
	ds_read2st64_b64 v[58:61], v65 offset0:4 offset1:5
	ds_read2st64_b64 v[84:87], v65 offset0:6 offset1:7
	s_waitcnt lgkmcnt(3)
	v_add_f32_e32 v13, 0, v50
	v_add_f32_e32 v17, 0, v51
	v_cndmask_b32_e32 v12, 0, v13, vcc
	v_cndmask_b32_e32 v16, 0, v17, vcc
	s_cselect_b64 vcc, -1, 0
	s_cmp_gt_i32 s76, 2
	v_cndmask_b32_e32 v24, 0, v52, vcc
	v_cndmask_b32_e32 v50, 0, v53, vcc
	s_cselect_b64 vcc, -1, 0
	s_cmp_gt_i32 s76, 3
	v_mov_b32_e32 v25, v52
	s_waitcnt lgkmcnt(2)
	v_cndmask_b32_e32 v90, 0, v54, vcc
	v_cndmask_b32_e32 v92, 0, v55, vcc
	s_cselect_b64 vcc, -1, 0
	s_cmp_gt_i32 s76, 4
	v_pk_add_f32 v[12:13], v[12:13], v[24:25]
	v_mov_b32_e32 v91, v54
	v_mov_b32_e32 v51, v53
	v_cndmask_b32_e32 v94, 0, v56, vcc
	v_cndmask_b32_e32 v96, 0, v57, vcc
	s_cselect_b64 vcc, -1, 0
	s_cmp_gt_i32 s76, 5
	v_pk_add_f32 v[12:13], v[12:13], v[90:91]
	v_mov_b32_e32 v95, v56
	v_pk_add_f32 v[16:17], v[16:17], v[50:51]
	v_mov_b32_e32 v93, v55
	s_waitcnt lgkmcnt(1)
	v_cndmask_b32_e32 v98, 0, v58, vcc
	v_cndmask_b32_e32 v100, 0, v59, vcc
	s_cselect_b64 vcc, -1, 0
	s_cmp_gt_i32 s76, 6
	v_pk_add_f32 v[12:13], v[12:13], v[94:95]
	v_mov_b32_e32 v99, v58
	v_pk_add_f32 v[16:17], v[16:17], v[92:93]
	v_mov_b32_e32 v97, v57
	v_cndmask_b32_e32 v102, 0, v60, vcc
	v_cndmask_b32_e32 v104, 0, v61, vcc
	s_cselect_b64 vcc, -1, 0
	s_cmp_gt_i32 s76, 7
	v_pk_add_f32 v[12:13], v[12:13], v[98:99]
	v_mov_b32_e32 v103, v60
	v_pk_add_f32 v[16:17], v[16:17], v[96:97]
	v_mov_b32_e32 v101, v59
	s_waitcnt lgkmcnt(0)
	v_cndmask_b32_e32 v106, 0, v84, vcc
	v_cndmask_b32_e32 v108, 0, v85, vcc
	s_cselect_b64 vcc, -1, 0
	v_pk_add_f32 v[12:13], v[12:13], v[102:103]
	v_mov_b32_e32 v107, v84
	v_pk_add_f32 v[16:17], v[16:17], v[100:101]
	v_mov_b32_e32 v105, v61
	v_cndmask_b32_e32 v110, 0, v86, vcc
	v_pk_add_f32 v[12:13], v[12:13], v[106:107]
	v_mov_b32_e32 v111, v86
	v_pk_add_f32 v[16:17], v[16:17], v[104:105]
	v_mov_b32_e32 v109, v85
	v_cndmask_b32_e32 v112, 0, v87, vcc
	v_pk_add_f32 v[12:13], v[12:13], v[110:111]
	v_pk_add_f32 v[16:17], v[16:17], v[108:109]
	v_mov_b32_e32 v113, v87
	v_pk_add_f32 v[16:17], v[16:17], v[112:113]
	v_add_f32_e32 v56, v62, v12
	v_mul_f32_e32 v24, 0x3fb8aa3b, v56
	v_add_f32_e32 v57, v63, v16
	v_exp_f32_e32 v50, v24
	v_mul_f32_e32 v24, 0x3fb8aa3b, v57
	v_exp_f32_e32 v51, v24
	v_lshlrev_b32_e32 v52, 16, v49
	v_and_b32_e32 v53, 0xffff0000, v49
	s_lshl_b32 s36, s77, 1
	v_pk_mul_f32 v[50:51], v[50:51], v[52:53]
	s_add_u32 s36, s66, s36
	v_cvt_pk_bf16_f32 v49, v50, v51
	v_fma_f32 v50, -0.5, v13, v56
	v_fma_f32 v51, -0.5, v17, v57
	v_min_f32_e32 v50, 0x42a00000, v50
	v_min_f32_e32 v51, 0x42a00000, v51
	v_mul_f32_e32 v50, 0x3fb8aa3b, v50
	v_mul_f32_e32 v51, 0x3fb8aa3b, v51
	v_exp_f32_e32 v50, v50
	v_exp_f32_e32 v51, v51
	s_addc_u32 s37, s67, 0
	v_lshl_add_u64 v[24:25], s[36:37], 0, v[76:77]
	s_lshl_b64 s[36:37], s[64:65], 11
	v_lshl_add_u64 v[54:55], v[24:25], 0, s[36:37]
	v_pk_mul_f32 v[50:51], v[50:51], v[52:53]
	flat_store_dword v[54:55], v49
	v_cvt_pk_bf16_f32 v49, v50, v51
	v_fma_f32 v50, v13, 0.5, -v56
	v_fma_f32 v51, v17, 0.5, -v57
	v_min_f32_e32 v50, 0x42a00000, v50
	v_min_f32_e32 v51, 0x42a00000, v51
	v_mul_f32_e32 v50, 0x3fb8aa3b, v50
	v_mul_f32_e32 v51, 0x3fb8aa3b, v51
	v_exp_f32_e32 v50, v50
	v_exp_f32_e32 v51, v51
	v_pk_add_f32 v[52:53], v[20:21], 1.0 op_sel_hi:[1,0] neg_lo:[1,0] neg_hi:[1,0]
	s_mul_i32 s36, s76, 0x880
	v_add_u32_e32 v54, s36, v67
	v_pk_mul_f32 v[20:21], v[52:53], v[50:51]
	v_add_f32_e32 v51, v89, v16
	v_cvt_pk_bf16_f32 v20, v20, v21
	v_sub_f32_e32 v21, v17, v57
	v_mul_f32_e32 v21, 0x3fb8aa3b, v21
	v_exp_f32_e32 v50, v21
	v_add_f32_e32 v21, v88, v12
	ds_write2st64_b32 v54, v49, v20 offset1:68
	v_mul_f32_e32 v49, 0x3fb8aa3b, v21
	v_exp_f32_e32 v54, v49
	v_mul_f32_e32 v49, 0x3fb8aa3b, v51
	v_exp_f32_e32 v55, v49
	v_sub_f32_e32 v20, v13, v56
	v_lshlrev_b32_e32 v56, 16, v48
	v_and_b32_e32 v57, 0xffff0000, v48
	v_pk_mul_f32 v[48:49], v[54:55], v[56:57]
	s_or_b32 s38, s55, 1
	v_cvt_pk_bf16_f32 v58, v48, v49
	v_fma_f32 v48, -0.5, v13, v21
	v_fma_f32 v49, -0.5, v17, v51
	v_min_f32_e32 v48, 0x42a00000, v48
	v_min_f32_e32 v49, 0x42a00000, v49
	v_mul_f32_e32 v48, 0x3fb8aa3b, v48
	v_mul_f32_e32 v49, 0x3fb8aa3b, v49
	s_ashr_i32 s37, s38, 31
	v_exp_f32_e32 v48, v48
	v_exp_f32_e32 v49, v49
	s_add_u32 s36, s60, s38
	s_addc_u32 s37, s61, s37
	s_lshl_b64 s[36:37], s[36:37], 11
	v_lshl_add_u64 v[54:55], v[24:25], 0, s[36:37]
	v_pk_mul_f32 v[48:49], v[48:49], v[56:57]
	flat_store_dword v[54:55], v58
	v_cvt_pk_bf16_f32 v54, v48, v49
	v_fma_f32 v48, v13, 0.5, -v21
	v_fma_f32 v49, v17, 0.5, -v51
	v_min_f32_e32 v48, 0x42a00000, v48
	v_min_f32_e32 v49, 0x42a00000, v49
	v_mul_f32_e32 v48, 0x3fb8aa3b, v48
	v_mul_f32_e32 v49, 0x3fb8aa3b, v49
	v_exp_f32_e32 v48, v48
	v_exp_f32_e32 v49, v49
	s_mulk_i32 s38, 0x110
	v_add_u32_e32 v55, s38, v67
	v_sub_f32_e32 v21, v13, v21
	v_pk_mul_f32 v[48:49], v[14:15], v[48:49]
	v_mul_f32_e32 v20, 0x3fb8aa3b, v20
	v_cvt_pk_bf16_f32 v48, v48, v49
	v_sub_f32_e32 v49, v17, v51
	v_mul_f32_e32 v49, 0x3fb8aa3b, v49
	ds_write_b32 v55, v48 offset:17408
	v_mul_f32_e32 v21, 0x3fb8aa3b, v21
	v_mov_b32_e32 v48, v52
	v_exp_f32_e32 v51, v49
	v_mov_b32_e32 v49, v14
	v_mov_b32_e32 v14, v53
	v_add_f32_e32 v52, v32, v12
	v_add_f32_e32 v53, v33, v16
	v_exp_f32_e32 v20, v20
	v_exp_f32_e32 v21, v21
	v_mul_f32_e32 v32, 0x3fb8aa3b, v52
	v_mul_f32_e32 v33, 0x3fb8aa3b, v53
	v_exp_f32_e32 v32, v32
	v_exp_f32_e32 v33, v33
	v_pk_mul_f32 v[20:21], v[48:49], v[20:21]
	s_or_b32 s36, s55, 2
	v_lshlrev_b32_e32 v48, 16, v47
	v_and_b32_e32 v49, 0xffff0000, v47
	v_pk_mul_f32 v[32:33], v[32:33], v[48:49]
	s_ashr_i32 s37, s36, 31
	v_cvt_pk_bf16_f32 v47, v32, v33
	s_add_u32 s36, s60, s36
	v_fma_f32 v32, -0.5, v13, v52
	v_fma_f32 v33, -0.5, v17, v53
	s_addc_u32 s37, s61, s37
	v_min_f32_e32 v32, 0x42a00000, v32
	v_min_f32_e32 v33, 0x42a00000, v33
	v_mul_f32_e32 v32, 0x3fb8aa3b, v32
	v_mul_f32_e32 v33, 0x3fb8aa3b, v33
	s_lshl_b64 s[36:37], s[36:37], 11
	v_pk_mul_f32 v[14:15], v[14:15], v[50:51]
	v_exp_f32_e32 v32, v32
	v_exp_f32_e32 v33, v33
	v_lshl_add_u64 v[50:51], v[24:25], 0, s[36:37]
	ds_write_b32 v55, v54
	flat_store_dword v[50:51], v47
	v_fma_f32 v47, v13, 0.5, -v52
	v_min_f32_e32 v47, 0x42a00000, v47
	v_mul_f32_e32 v47, 0x3fb8aa3b, v47
	v_pk_mul_f32 v[32:33], v[32:33], v[48:49]
	v_exp_f32_e32 v48, v47
	v_fma_f32 v47, v17, 0.5, -v53
	v_min_f32_e32 v47, 0x42a00000, v47
	v_mul_f32_e32 v47, 0x3fb8aa3b, v47
	v_exp_f32_e32 v49, v47
	v_cvt_pk_bf16_f32 v32, v32, v33
	ds_write_b32 v55, v32 offset:272
	v_pk_add_f32 v[32:33], v[10:11], 1.0 op_sel_hi:[1,0] neg_lo:[1,0] neg_hi:[1,0]
	s_or_b32 s36, s55, 3
	v_pk_mul_f32 v[10:11], v[32:33], v[48:49]
	v_add_f32_e32 v49, v31, v16
	v_cvt_pk_bf16_f32 v10, v10, v11
	v_sub_f32_e32 v11, v17, v53
	v_mul_f32_e32 v11, 0x3fb8aa3b, v11
	v_exp_f32_e32 v48, v11
	v_add_f32_e32 v11, v30, v12
	v_mul_f32_e32 v30, 0x3fb8aa3b, v11
	v_mul_f32_e32 v31, 0x3fb8aa3b, v49
	v_exp_f32_e32 v30, v30
	v_exp_f32_e32 v31, v31
	s_ashr_i32 s37, s36, 31
	v_lshlrev_b32_e32 v50, 16, v46
	v_and_b32_e32 v51, 0xffff0000, v46
	s_add_u32 s36, s60, s36
	v_pk_mul_f32 v[30:31], v[30:31], v[50:51]
	s_addc_u32 s37, s61, s37
	ds_write_b32 v55, v10 offset:17680
	v_sub_f32_e32 v10, v13, v52
	v_cvt_pk_bf16_f32 v52, v30, v31
	v_fma_f32 v30, -0.5, v13, v11
	v_fma_f32 v31, -0.5, v17, v49
	s_lshl_b64 s[36:37], s[36:37], 11
	v_min_f32_e32 v30, 0x42a00000, v30
	v_min_f32_e32 v31, 0x42a00000, v31
	v_lshl_add_u64 v[46:47], v[24:25], 0, s[36:37]
	v_mul_f32_e32 v30, 0x3fb8aa3b, v30
	v_mul_f32_e32 v31, 0x3fb8aa3b, v31
	flat_store_dword v[46:47], v52
	v_fma_f32 v46, v13, 0.5, -v11
	v_fma_f32 v47, v17, 0.5, -v49
	v_exp_f32_e32 v30, v30
	v_exp_f32_e32 v31, v31
	v_min_f32_e32 v46, 0x42a00000, v46
	v_min_f32_e32 v47, 0x42a00000, v47
	v_mul_f32_e32 v46, 0x3fb8aa3b, v46
	v_mul_f32_e32 v47, 0x3fb8aa3b, v47
	v_exp_f32_e32 v46, v46
	v_exp_f32_e32 v47, v47
	v_pk_mul_f32 v[30:31], v[30:31], v[50:51]
	v_sub_f32_e32 v11, v13, v11
	v_cvt_pk_bf16_f32 v30, v30, v31
	v_mul_f32_e32 v10, 0x3fb8aa3b, v10
	ds_write_b32 v55, v30 offset:544
	v_pk_mul_f32 v[30:31], v[8:9], v[46:47]
	v_mul_f32_e32 v11, 0x3fb8aa3b, v11
	v_add_f32_e32 v46, v28, v12
	v_add_f32_e32 v47, v29, v16
	v_exp_f32_e32 v10, v10
	v_exp_f32_e32 v11, v11
	v_mul_f32_e32 v28, 0x3fb8aa3b, v46
	v_mul_f32_e32 v29, 0x3fb8aa3b, v47
	v_cvt_pk_bf16_f32 v30, v30, v31
	v_sub_f32_e32 v31, v17, v49
	v_exp_f32_e32 v28, v28
	v_exp_f32_e32 v29, v29
	v_mul_f32_e32 v31, 0x3fb8aa3b, v31
	ds_write_b32 v55, v30 offset:17952
	v_mov_b32_e32 v30, v32
	v_exp_f32_e32 v49, v31
	v_mov_b32_e32 v31, v8
	v_pk_mul_f32 v[10:11], v[30:31], v[10:11]
	v_lshlrev_b32_e32 v30, 16, v45
	v_and_b32_e32 v31, 0xffff0000, v45
	v_pk_mul_f32 v[28:29], v[28:29], v[30:31]
	s_or_b32 s36, s55, 4
	v_cvt_pk_bf16_f32 v45, v28, v29
	v_fma_f32 v28, -0.5, v13, v46
	v_fma_f32 v29, -0.5, v17, v47
	v_min_f32_e32 v28, 0x42a00000, v28
	v_min_f32_e32 v29, 0x42a00000, v29
	v_mul_f32_e32 v28, 0x3fb8aa3b, v28
	v_mul_f32_e32 v29, 0x3fb8aa3b, v29
	v_exp_f32_e32 v28, v28
	v_exp_f32_e32 v29, v29
	s_ashr_i32 s37, s36, 31
	s_add_u32 s36, s60, s36
	s_addc_u32 s37, s61, s37
	v_pk_mul_f32 v[28:29], v[28:29], v[30:31]
	v_fma_f32 v30, v13, 0.5, -v46
	v_fma_f32 v31, v17, 0.5, -v47
	v_min_f32_e32 v30, 0x42a00000, v30
	v_min_f32_e32 v31, 0x42a00000, v31
	v_mul_f32_e32 v30, 0x3fb8aa3b, v30
	v_mul_f32_e32 v31, 0x3fb8aa3b, v31
	v_exp_f32_e32 v30, v30
	v_exp_f32_e32 v31, v31
	s_lshl_b64 s[36:37], s[36:37], 11
	v_mov_b32_e32 v8, v33
	v_lshl_add_u64 v[32:33], v[24:25], 0, s[36:37]
	v_cvt_pk_bf16_f32 v28, v28, v29
	flat_store_dword v[32:33], v45
	ds_write_b32 v55, v28 offset:816
	v_pk_mul_f32 v[28:29], v[6:7], v[30:31]
	v_add_f32_e32 v31, v27, v16
	v_cvt_pk_bf16_f32 v28, v28, v29
	v_sub_f32_e32 v29, v17, v47
	v_mul_f32_e32 v29, 0x3fb8aa3b, v29
	v_exp_f32_e32 v30, v29
	v_add_f32_e32 v29, v26, v12
	v_mul_f32_e32 v26, 0x3fb8aa3b, v29
	v_mul_f32_e32 v27, 0x3fb8aa3b, v31
	v_exp_f32_e32 v26, v26
	v_exp_f32_e32 v27, v27
	v_lshlrev_b32_e32 v32, 16, v44
	v_and_b32_e32 v33, 0xffff0000, v44
	ds_write_b32 v55, v28 offset:18224
	v_pk_mul_f32 v[26:27], v[26:27], v[32:33]
	v_sub_f32_e32 v28, v13, v46
	v_cvt_pk_bf16_f32 v46, v26, v27
	v_fma_f32 v26, -0.5, v13, v29
	v_fma_f32 v27, -0.5, v17, v31
	v_min_f32_e32 v26, 0x42a00000, v26
	v_min_f32_e32 v27, 0x42a00000, v27
	v_mul_f32_e32 v26, 0x3fb8aa3b, v26
	v_mul_f32_e32 v27, 0x3fb8aa3b, v27
	v_exp_f32_e32 v26, v26
	v_exp_f32_e32 v27, v27
	s_or_b32 s36, s55, 5
	s_ashr_i32 s37, s36, 31
	s_add_u32 s36, s60, s36
	v_pk_mul_f32 v[26:27], v[26:27], v[32:33]
	v_fma_f32 v32, v13, 0.5, -v29
	v_fma_f32 v33, v17, 0.5, -v31
	v_min_f32_e32 v32, 0x42a00000, v32
	v_min_f32_e32 v33, 0x42a00000, v33
	v_mul_f32_e32 v32, 0x3fb8aa3b, v32
	v_mul_f32_e32 v33, 0x3fb8aa3b, v33
	v_exp_f32_e32 v32, v32
	v_exp_f32_e32 v33, v33
	s_addc_u32 s37, s61, s37
	s_lshl_b64 s[36:37], s[36:37], 11
	v_lshl_add_u64 v[44:45], v[24:25], 0, s[36:37]
	v_cvt_pk_bf16_f32 v26, v26, v27
	flat_store_dword v[44:45], v46
	ds_write_b32 v55, v26 offset:1088
	v_pk_mul_f32 v[26:27], v[4:5], v[32:33]
	v_mul_f32_e32 v28, 0x3fb8aa3b, v28
	v_cvt_pk_bf16_f32 v26, v26, v27
	ds_write_b32 v55, v26 offset:18496
	v_sub_f32_e32 v26, v13, v29
	v_mul_f32_e32 v26, 0x3fb8aa3b, v26
	v_exp_f32_e32 v29, v26
	v_mov_b32_e32 v26, v6
	v_sub_f32_e32 v6, v17, v31
	v_mul_f32_e32 v6, 0x3fb8aa3b, v6
	v_exp_f32_e32 v31, v6
	v_mov_b32_e32 v27, v4
	v_mov_b32_e32 v4, v7
	s_or_b32 s36, s55, 6
	v_pk_mul_f32 v[4:5], v[4:5], v[30:31]
	v_add_f32_e32 v30, v22, v12
	v_add_f32_e32 v31, v23, v16
	v_mul_f32_e32 v6, 0x3fb8aa3b, v30
	v_mul_f32_e32 v7, 0x3fb8aa3b, v31
	v_exp_f32_e32 v6, v6
	v_exp_f32_e32 v7, v7
	v_lshlrev_b32_e32 v22, 16, v43
	v_and_b32_e32 v23, 0xffff0000, v43
	v_exp_f32_e32 v28, v28
	v_pk_mul_f32 v[6:7], v[6:7], v[22:23]
	s_ashr_i32 s37, s36, 31
	v_cvt_pk_bf16_f32 v32, v6, v7
	v_fma_f32 v6, -0.5, v13, v30
	v_fma_f32 v7, -0.5, v17, v31
	v_min_f32_e32 v6, 0x42a00000, v6
	v_min_f32_e32 v7, 0x42a00000, v7
	v_mul_f32_e32 v6, 0x3fb8aa3b, v6
	v_mul_f32_e32 v7, 0x3fb8aa3b, v7
	v_exp_f32_e32 v6, v6
	v_exp_f32_e32 v7, v7
	s_add_u32 s36, s60, s36
	s_addc_u32 s37, s61, s37
	s_lshl_b64 s[36:37], s[36:37], 11
	v_pk_mul_f32 v[6:7], v[6:7], v[22:23]
	v_fma_f32 v22, v13, 0.5, -v30
	v_fma_f32 v23, v17, 0.5, -v31
	v_min_f32_e32 v22, 0x42a00000, v22
	v_min_f32_e32 v23, 0x42a00000, v23
	v_mul_f32_e32 v22, 0x3fb8aa3b, v22
	v_mul_f32_e32 v23, 0x3fb8aa3b, v23
	v_exp_f32_e32 v22, v22
	v_exp_f32_e32 v23, v23
	v_pk_mul_f32 v[26:27], v[26:27], v[28:29]
	v_lshl_add_u64 v[28:29], v[24:25], 0, s[36:37]
	v_cvt_pk_bf16_f32 v6, v6, v7
	flat_store_dword v[28:29], v32
	ds_write_b32 v55, v6 offset:1360
	v_pk_mul_f32 v[6:7], v[2:3], v[22:23]
	s_or_b32 s36, s55, 7
	v_cvt_pk_bf16_f32 v6, v6, v7
	v_sub_f32_e32 v7, v17, v31
	v_mul_f32_e32 v7, 0x3fb8aa3b, v7
	v_exp_f32_e32 v22, v7
	v_add_f32_e32 v7, v18, v12
	v_add_f32_e32 v12, v19, v16
	v_mul_f32_e32 v16, 0x3fb8aa3b, v7
	v_exp_f32_e32 v18, v16
	v_mul_f32_e32 v16, 0x3fb8aa3b, v12
	v_exp_f32_e32 v19, v16
	s_ashr_i32 s37, s36, 31
	s_add_u32 s36, s60, s36
	v_lshlrev_b32_e32 v28, 16, v42
	v_and_b32_e32 v29, 0xffff0000, v42
	s_addc_u32 s37, s61, s37
	v_pk_mul_f32 v[18:19], v[18:19], v[28:29]
	s_lshl_b64 s[36:37], s[36:37], 11
	v_cvt_pk_bf16_f32 v16, v18, v19
	v_lshl_add_u64 v[24:25], v[24:25], 0, s[36:37]
	ds_write_b32 v55, v6 offset:18768
	flat_store_dword v[24:25], v16
	v_fma_f32 v16, v13, 0.5, -v7
	v_min_f32_e32 v16, 0x42a00000, v16
	v_fma_f32 v18, -0.5, v13, v7
	v_fma_f32 v19, -0.5, v17, v12
	v_mul_f32_e32 v16, 0x3fb8aa3b, v16
	v_min_f32_e32 v18, 0x42a00000, v18
	v_min_f32_e32 v19, 0x42a00000, v19
	v_exp_f32_e32 v24, v16
	v_fma_f32 v16, v17, 0.5, -v12
	v_mul_f32_e32 v18, 0x3fb8aa3b, v18
	v_mul_f32_e32 v19, 0x3fb8aa3b, v19
	v_min_f32_e32 v16, 0x42a00000, v16
	v_exp_f32_e32 v18, v18
	v_exp_f32_e32 v19, v19
	v_mul_f32_e32 v16, 0x3fb8aa3b, v16
	v_exp_f32_e32 v25, v16
	v_sub_f32_e32 v6, v13, v30
	v_pk_mul_f32 v[18:19], v[18:19], v[28:29]
	v_sub_f32_e32 v7, v13, v7
	v_cvt_pk_bf16_f32 v16, v18, v19
	v_pk_mul_f32 v[18:19], v[0:1], v[24:25]
	v_mul_f32_e32 v6, 0x3fb8aa3b, v6
	ds_write_b32 v55, v16 offset:1632
	v_cvt_pk_bf16_f32 v16, v18, v19
	v_mul_f32_e32 v7, 0x3fb8aa3b, v7
	v_mov_b32_e32 v18, v2
	v_sub_f32_e32 v2, v17, v12
	v_exp_f32_e32 v6, v6
	v_exp_f32_e32 v7, v7
	v_mul_f32_e32 v2, 0x3fb8aa3b, v2
	v_exp_f32_e32 v23, v2
	v_mov_b32_e32 v19, v0
	v_pk_mul_f32 v[6:7], v[18:19], v[6:7]
	v_mov_b32_e32 v0, v3
	v_pk_mul_f32 v[8:9], v[8:9], v[48:49]
	v_pk_mul_f32 v[18:19], v[0:1], v[22:23]
	v_cvt_pk_bf16_f32 v0, v20, v21
	v_cvt_pk_bf16_f32 v1, v10, v11
	v_cvt_pk_bf16_f32 v2, v26, v27
	v_cvt_pk_bf16_f32 v3, v6, v7
	v_lshl_add_u32 v6, s76, 4, v69
	ds_write_b32 v55, v16 offset:19040
	ds_write_b128 v6, v[0:3] offset:34816
	v_cvt_pk_bf16_f32 v0, v14, v15
	v_cvt_pk_bf16_f32 v1, v8, v9
	v_cvt_pk_bf16_f32 v2, v4, v5
	v_cvt_pk_bf16_f32 v3, v18, v19
	ds_write_b128 v6, v[0:3] offset:34960
	v_and_b32_e32 v0, 0xffff, v34
	v_and_b32_e32 v1, 0xffff, v36
	v_and_b32_e32 v2, 0xffff, v38
	v_and_b32_e32 v3, 0xffff, v40
	v_lshl_or_b32 v0, v35, 16, v0
	v_lshl_or_b32 v1, v37, 16, v1
	v_lshl_or_b32 v2, v39, 16, v2
	v_lshl_or_b32 v3, v41, 16, v3
	ds_write_b128 v6, v[0:3] offset:53248
	v_lshrrev_b32_e32 v0, 16, v34
	v_lshrrev_b32_e32 v1, 16, v36
	v_lshrrev_b32_e32 v2, 16, v38
	v_lshrrev_b32_e32 v3, 16, v40
	v_and_or_b32 v0, v35, s74, v0
	v_and_or_b32 v1, v37, s74, v1
	v_and_or_b32 v2, v39, s74, v2
	v_and_or_b32 v3, v41, s74, v3
	s_cmp_lg_u32 s76, 7
	ds_write_b128 v6, v[0:3] offset:53392
	s_cbranch_scc1 .LBB0_954
	v_mul_f32_e32 v0, 0x3fb8aa3b, v13
	v_mul_f32_e32 v1, 0x3fb8aa3b, v17
	s_ashr_i32 s55, s54, 31
	v_exp_f32_e32 v0, v0
	v_exp_f32_e32 v1, v1
	s_lshl_b64 s[36:37], s[54:55], 9
	s_add_u32 s36, s62, s36
	s_addc_u32 s37, s63, s37
	v_lshlrev_b32_e32 v2, 2, v68
	v_mov_b32_e32 v3, v71
	v_lshl_add_u64 v[2:3], s[36:37], 0, v[2:3]
	flat_store_dwordx2 v[2:3], v[0:1]
